# dropped the full vmcnt wait after hoisted weight loads in pool/fourier_out preambles (first in-loop counted wait covers them)
# baseline (speedup 1.0000x reference)
.LBB0_233:
	v_mov_b32_e32 v0, v242
	s_load_dword s11, s[54:55], 0x0
	s_mov_b32 s9, s76
	v_readfirstlane_b32 s0, v0
	s_waitcnt lgkmcnt(0)
	s_ashr_i32 s17, s0, 6
	s_lshl_b32 s0, s9, 3
	s_lshl_b32 s2, s56, 19
	s_add_i32 s0, s0, s17
	s_cmpk_gt_i32 s0, 0xfff
	s_cbranch_scc1 .LBB0_237
	s_lshl_b32 s3, s11, 3
	v_readlane_b32 s16, v253, 8
	v_and_b32_e32 v136, 15, v0
	s_add_u32 s18, s16, s2
	v_readlane_b32 s16, v253, 9
	s_mul_i32 s20, s17, 0x4200
	s_addc_u32 s19, s16, 0
	s_add_i32 s20, s20, 0
	v_mul_u32_u24_e32 v3, 0x210, v136
	v_and_b32_e32 v208, 48, v0
	v_lshl_add_u64 v[4:5], s[18:19], 0, v[208:209]
	v_add3_u32 v149, s20, v3, v208
	v_lshlrev_b32_e32 v208, 7, v136
	v_lshl_add_u64 v[72:73], v[4:5], 0, v[208:209]
	s_mov_b64 s[18:19], 0x1800
	v_lshl_add_u64 v[76:77], v[72:73], 0, s[18:19]
	s_mov_b64 s[18:19], 0x1040
	v_lshl_add_u64 v[78:79], v[72:73], 0, s[18:19]
	s_mov_b64 s[18:19], 0x1840
	v_lshl_add_u64 v[80:81], v[72:73], 0, s[18:19]
	s_mov_b64 s[18:19], 0x2000
	v_lshl_add_u64 v[82:83], v[72:73], 0, s[18:19]
	s_mov_b64 s[18:19], 0x2800
	v_lshl_add_u64 v[84:85], v[72:73], 0, s[18:19]
	s_mov_b64 s[18:19], 0x3000
	v_lshl_add_u64 v[86:87], v[72:73], 0, s[18:19]
	s_mov_b64 s[18:19], 0x3800
	v_lshl_add_u64 v[88:89], v[72:73], 0, s[18:19]
	s_mov_b64 s[18:19], 0x2040
	v_lshl_add_u64 v[90:91], v[72:73], 0, s[18:19]
	s_mov_b64 s[18:19], 0x2840
	v_lshl_add_u64 v[92:93], v[72:73], 0, s[18:19]
	s_mov_b64 s[18:19], 0x3040
	v_lshl_add_u64 v[94:95], v[72:73], 0, s[18:19]
	s_mov_b64 s[18:19], 0x3840
	v_lshl_add_u64 v[96:97], v[72:73], 0, s[18:19]
	s_mov_b64 s[18:19], 0x4000
	v_lshl_add_u64 v[98:99], v[72:73], 0, s[18:19]
	s_mov_b64 s[18:19], 0x4800
	v_lshl_add_u64 v[100:101], v[72:73], 0, s[18:19]
	s_mov_b64 s[18:19], 0x5000
	v_lshl_add_u64 v[102:103], v[72:73], 0, s[18:19]
	s_mov_b64 s[18:19], 0x5800
	v_lshl_add_u64 v[104:105], v[72:73], 0, s[18:19]
	s_mov_b64 s[18:19], 0x4040
	v_lshl_add_u64 v[106:107], v[72:73], 0, s[18:19]
	s_mov_b64 s[18:19], 0x4840
	v_lshl_add_u64 v[108:109], v[72:73], 0, s[18:19]
	s_mov_b64 s[18:19], 0x5040
	v_lshl_add_u64 v[110:111], v[72:73], 0, s[18:19]
	s_mov_b64 s[18:19], 0x5840
	v_lshl_add_u64 v[112:113], v[72:73], 0, s[18:19]
	s_mov_b64 s[18:19], 0x6000
	v_lshl_add_u64 v[114:115], v[72:73], 0, s[18:19]
	s_mov_b64 s[18:19], 0x6800
	v_lshl_add_u64 v[116:117], v[72:73], 0, s[18:19]
	s_mov_b64 s[18:19], 0x7000
	v_lshl_add_u64 v[118:119], v[72:73], 0, s[18:19]
	s_mov_b64 s[18:19], 0x7800
	v_lshlrev_b32_e32 v1, 3, v0
	v_lshl_add_u64 v[120:121], v[72:73], 0, s[18:19]
	s_mov_b64 s[18:19], 0x6040
	v_and_b32_e32 v2, 0xf8, v1
	v_lshlrev_b32_e32 v1, 4, v0
	v_lshl_add_u64 v[122:123], v[72:73], 0, s[18:19]
	s_mov_b64 s[18:19], 0x6840
	v_bfe_u32 v137, v0, 5, 1
	v_and_b32_e32 v1, 0x1f0, v1
	v_lshrrev_b32_e32 v0, 2, v0
	v_lshl_add_u64 v[124:125], v[72:73], 0, s[18:19]
	s_mov_b64 s[18:19], 0x7040
	v_add_u32_e32 v1, s20, v1
	v_and_b32_e32 v0, 12, v0
	v_mul_u32_u24_e32 v6, 0x210, v137
	v_lshl_add_u64 v[126:127], v[72:73], 0, s[18:19]
	s_mov_b64 s[18:19], 0x7840
	s_lshl_b32 s9, s9, 7
	s_lshl_b32 s17, s17, 4
	v_or_b32_e32 v138, 10, v137
	v_or_b32_e32 v139, 12, v137
	v_or_b32_e32 v140, 14, v137
	v_or_b32_e32 v141, 16, v137
	v_or_b32_e32 v142, 18, v137
	v_or_b32_e32 v143, 20, v137
	v_or_b32_e32 v144, 22, v137
	v_or_b32_e32 v145, 24, v137
	v_or_b32_e32 v146, 26, v137
	v_or_b32_e32 v147, 28, v137
	v_or_b32_e32 v148, 30, v137
	v_lshl_add_u64 v[74:75], v[72:73], 0, s[38:39]
	v_lshl_add_u64 v[128:129], v[72:73], 0, s[18:19]
	s_add_i32 s9, s9, s17
	s_lshl_b32 s17, s11, 7
	v_lshlrev_b32_e32 v130, 1, v2
	v_add_u32_e32 v150, v1, v6
	v_lshlrev_b32_e32 v132, 1, v0
	s_mov_b32 s16, 0xbff9000
	global_load_dwordx4 v[166:169], v[72:73], off offset:64
	global_load_dwordx4 v[170:173], v[72:73], off offset:2112
	global_load_dwordx4 v[174:177], v[78:79], off
	global_load_dwordx4 v[178:181], v[80:81], off
	global_load_dwordx4 v[182:185], v[90:91], off
	global_load_dwordx4 v[186:189], v[92:93], off
	global_load_dwordx4 v[190:193], v[94:95], off
	global_load_dwordx4 v[194:197], v[96:97], off
	global_load_dwordx4 v[198:201], v[106:107], off
	global_load_dwordx4 v[202:205], v[108:109], off
	global_load_dwordx4 v[214:217], v[110:111], off
	global_load_dwordx4 v[218:221], v[112:113], off
	global_load_dwordx4 v[222:225], v[122:123], off
	global_load_dwordx4 v[226:229], v[124:125], off
	global_load_dwordx4 v[230:233], v[126:127], off
	global_load_dwordx4 v[234:237], v[128:129], off
.LBB0_235:
	global_load_dwordx4 v[90:93], v[74:75], off
	global_load_dwordx4 v[94:97], v[72:73], off
	global_load_dwordx4 v[106:109], v[72:73], off offset:2048
	global_load_dwordx4 v[110:113], v[76:77], off
	v_add_u32_e32 v56, s9, v137
	v_mov_b32_e32 v131, v209
	s_ashr_i32 s11, s9, 31
	s_lshr_b32 s11, s11, 19
	s_add_i32 s11, s9, s11
	s_and_b32 s11, s11, 0xffffe000
	s_sub_i32 s11, s9, s11
	s_add_i32 s18, s11, -8
	s_add_i32 s0, s0, s3
	s_add_u32 s100, s84, s58
	s_addc_u32 s101, s85, 0
	v_add_u32_e32 v0, 0, v56
	v_max_i32_e32 v0, 8, v0
	v_add_u32_e32 v0, -8, v0
	v_min_u32_e32 v0, 0xffff, v0
	v_mul_u32_u24_e32 v208, 0xe00, v0
	v_lshl_add_u64 v[0:1], s[100:101], 0, v[208:209]
	v_lshl_add_u64 v[0:1], v[0:1], 0, v[130:131]
	global_load_dwordx4 v[0:3], v[0:1], off offset:1536
	v_add_u32_e32 v4, 2, v56
	v_max_i32_e32 v4, 8, v4
	v_add_u32_e32 v4, -8, v4
	v_min_u32_e32 v4, 0xffff, v4
	v_mul_u32_u24_e32 v208, 0xe00, v4
	v_lshl_add_u64 v[4:5], s[100:101], 0, v[208:209]
	v_lshl_add_u64 v[4:5], v[4:5], 0, v[130:131]
	global_load_dwordx4 v[4:7], v[4:5], off offset:1536
	v_add_u32_e32 v8, 4, v56
	v_max_i32_e32 v8, 8, v8
	v_add_u32_e32 v8, -8, v8
	v_min_u32_e32 v8, 0xffff, v8
	v_mul_u32_u24_e32 v208, 0xe00, v8
	v_lshl_add_u64 v[8:9], s[100:101], 0, v[208:209]
	v_lshl_add_u64 v[8:9], v[8:9], 0, v[130:131]
	global_load_dwordx4 v[8:11], v[8:9], off offset:1536
	v_add_u32_e32 v12, 6, v56
	v_max_i32_e32 v12, 8, v12
	v_add_u32_e32 v12, -8, v12
	v_min_u32_e32 v12, 0xffff, v12
	v_mul_u32_u24_e32 v208, 0xe00, v12
	v_lshl_add_u64 v[12:13], s[100:101], 0, v[208:209]
	v_lshl_add_u64 v[12:13], v[12:13], 0, v[130:131]
	global_load_dwordx4 v[12:15], v[12:13], off offset:1536
	v_add_u32_e32 v16, 8, v56
	v_max_i32_e32 v16, 8, v16
	v_add_u32_e32 v16, -8, v16
	v_min_u32_e32 v16, 0xffff, v16
	v_mul_u32_u24_e32 v208, 0xe00, v16
	v_lshl_add_u64 v[16:17], s[100:101], 0, v[208:209]
	v_lshl_add_u64 v[16:17], v[16:17], 0, v[130:131]
	global_load_dwordx4 v[16:19], v[16:17], off offset:1536
	v_add_u32_e32 v20, 10, v56
	v_max_i32_e32 v20, 8, v20
	v_add_u32_e32 v20, -8, v20
	v_min_u32_e32 v20, 0xffff, v20
	v_mul_u32_u24_e32 v208, 0xe00, v20
	v_lshl_add_u64 v[20:21], s[100:101], 0, v[208:209]
	v_lshl_add_u64 v[20:21], v[20:21], 0, v[130:131]
	global_load_dwordx4 v[20:23], v[20:21], off offset:1536
	v_add_u32_e32 v24, 12, v56
	v_max_i32_e32 v24, 8, v24
	v_add_u32_e32 v24, -8, v24
	v_min_u32_e32 v24, 0xffff, v24
	v_mul_u32_u24_e32 v208, 0xe00, v24
	v_lshl_add_u64 v[24:25], s[100:101], 0, v[208:209]
	v_lshl_add_u64 v[24:25], v[24:25], 0, v[130:131]
	global_load_dwordx4 v[24:27], v[24:25], off offset:1536
	v_add_u32_e32 v28, 14, v56
	v_max_i32_e32 v28, 8, v28
	v_add_u32_e32 v28, -8, v28
	v_min_u32_e32 v28, 0xffff, v28
	v_mul_u32_u24_e32 v208, 0xe00, v28
	v_lshl_add_u64 v[28:29], s[100:101], 0, v[208:209]
	v_lshl_add_u64 v[28:29], v[28:29], 0, v[130:131]
	global_load_dwordx4 v[28:31], v[28:29], off offset:1536
	v_add_u32_e32 v32, 16, v56
	v_max_i32_e32 v32, 8, v32
	v_add_u32_e32 v32, -8, v32
	v_min_u32_e32 v32, 0xffff, v32
	v_mul_u32_u24_e32 v208, 0xe00, v32
	v_lshl_add_u64 v[32:33], s[100:101], 0, v[208:209]
	v_lshl_add_u64 v[32:33], v[32:33], 0, v[130:131]
	global_load_dwordx4 v[32:35], v[32:33], off offset:1536
	v_add_u32_e32 v36, 18, v56
	v_max_i32_e32 v36, 8, v36
	v_add_u32_e32 v36, -8, v36
	v_min_u32_e32 v36, 0xffff, v36
	v_mul_u32_u24_e32 v208, 0xe00, v36
	v_lshl_add_u64 v[36:37], s[100:101], 0, v[208:209]
	v_lshl_add_u64 v[36:37], v[36:37], 0, v[130:131]
	global_load_dwordx4 v[36:39], v[36:37], off offset:1536
	v_add_u32_e32 v40, 20, v56
	v_max_i32_e32 v40, 8, v40
	v_add_u32_e32 v40, -8, v40
	v_min_u32_e32 v40, 0xffff, v40
	v_mul_u32_u24_e32 v208, 0xe00, v40
	v_lshl_add_u64 v[40:41], s[100:101], 0, v[208:209]
	v_lshl_add_u64 v[40:41], v[40:41], 0, v[130:131]
	global_load_dwordx4 v[40:43], v[40:41], off offset:1536
	v_add_u32_e32 v44, 22, v56
	v_max_i32_e32 v44, 8, v44
	v_add_u32_e32 v44, -8, v44
	v_min_u32_e32 v44, 0xffff, v44
	v_mul_u32_u24_e32 v208, 0xe00, v44
	v_lshl_add_u64 v[44:45], s[100:101], 0, v[208:209]
	v_lshl_add_u64 v[44:45], v[44:45], 0, v[130:131]
	global_load_dwordx4 v[44:47], v[44:45], off offset:1536
	v_add_u32_e32 v48, 24, v56
	v_max_i32_e32 v48, 8, v48
	v_add_u32_e32 v48, -8, v48
	v_min_u32_e32 v48, 0xffff, v48
	v_mul_u32_u24_e32 v208, 0xe00, v48
	v_lshl_add_u64 v[48:49], s[100:101], 0, v[208:209]
	v_lshl_add_u64 v[48:49], v[48:49], 0, v[130:131]
	global_load_dwordx4 v[48:51], v[48:49], off offset:1536
	v_add_u32_e32 v52, 26, v56
	v_max_i32_e32 v52, 8, v52
	v_add_u32_e32 v52, -8, v52
	v_min_u32_e32 v52, 0xffff, v52
	v_mul_u32_u24_e32 v208, 0xe00, v52
	v_lshl_add_u64 v[52:53], s[100:101], 0, v[208:209]
	v_lshl_add_u64 v[52:53], v[52:53], 0, v[130:131]
	global_load_dwordx4 v[52:55], v[52:53], off offset:1536
	v_add_u32_e32 v58, 28, v56
	v_max_i32_e32 v58, 8, v58
	v_add_u32_e32 v58, -8, v58
	v_min_u32_e32 v58, 0xffff, v58
	v_mul_u32_u24_e32 v208, 0xe00, v58
	v_lshl_add_u64 v[58:59], s[100:101], 0, v[208:209]
	v_lshl_add_u64 v[58:59], v[58:59], 0, v[130:131]
	global_load_dwordx4 v[58:61], v[58:59], off offset:1536
	v_add_u32_e32 v62, 30, v56
	v_max_i32_e32 v62, 8, v62
	v_add_u32_e32 v62, -8, v62
	v_min_u32_e32 v62, 0xffff, v62
	v_mul_u32_u24_e32 v208, 0xe00, v62
	v_lshl_add_u64 v[62:63], s[100:101], 0, v[208:209]
	v_lshl_add_u64 v[62:63], v[62:63], 0, v[130:131]
	global_load_dwordx4 v[62:65], v[62:63], off offset:1536
	s_cmpk_lt_u32 s18, 0x2000
	s_cselect_b64 vcc, -1, 0
	s_waitcnt vmcnt(15)
	v_cndmask_b32_e32 v3, 0, v3, vcc
	v_cndmask_b32_e32 v2, 0, v2, vcc
	v_cndmask_b32_e32 v1, 0, v1, vcc
	v_cndmask_b32_e32 v0, 0, v0, vcc
	s_waitcnt vmcnt(14)
	v_cndmask_b32_e32 v7, 0, v7, vcc
	v_cndmask_b32_e32 v6, 0, v6, vcc
	v_cndmask_b32_e32 v5, 0, v5, vcc
	v_cndmask_b32_e32 v4, 0, v4, vcc
	s_waitcnt vmcnt(13)
	v_cndmask_b32_e32 v11, 0, v11, vcc
	v_cndmask_b32_e32 v10, 0, v10, vcc
	v_cndmask_b32_e32 v9, 0, v9, vcc
	v_cndmask_b32_e32 v8, 0, v8, vcc
	s_waitcnt vmcnt(12)
	v_cndmask_b32_e32 v15, 0, v15, vcc
	v_cndmask_b32_e32 v14, 0, v14, vcc
	v_cndmask_b32_e32 v13, 0, v13, vcc
	v_cndmask_b32_e32 v12, 0, v12, vcc
	s_cmp_gt_i32 s11, -1
	s_cselect_b64 vcc, -1, 0
	s_waitcnt vmcnt(11)
	v_cndmask_b32_e32 v19, 0, v19, vcc
	v_cndmask_b32_e32 v18, 0, v18, vcc
	v_cndmask_b32_e32 v17, 0, v17, vcc
	v_cndmask_b32_e32 v16, 0, v16, vcc
	v_add_u32_e32 v206, s18, v138
	v_cmp_gt_u32_e32 vcc, s15, v206
	s_waitcnt vmcnt(10)
	s_nop 0
	v_cndmask_b32_e32 v23, 0, v23, vcc
	v_cndmask_b32_e32 v22, 0, v22, vcc
	v_cndmask_b32_e32 v21, 0, v21, vcc
	v_cndmask_b32_e32 v20, 0, v20, vcc
	v_add_u32_e32 v206, s18, v139
	v_cmp_gt_u32_e32 vcc, s15, v206
	s_waitcnt vmcnt(9)
	s_nop 0
	v_cndmask_b32_e32 v27, 0, v27, vcc
	v_cndmask_b32_e32 v26, 0, v26, vcc
	v_cndmask_b32_e32 v25, 0, v25, vcc
	v_cndmask_b32_e32 v24, 0, v24, vcc
	v_add_u32_e32 v206, s18, v140
	v_cmp_gt_u32_e32 vcc, s15, v206
	s_waitcnt vmcnt(8)
	s_nop 0
	v_cndmask_b32_e32 v31, 0, v31, vcc
	v_cndmask_b32_e32 v30, 0, v30, vcc
	v_cndmask_b32_e32 v29, 0, v29, vcc
	v_cndmask_b32_e32 v28, 0, v28, vcc
	v_add_u32_e32 v206, s18, v141
	v_cmp_gt_u32_e32 vcc, s15, v206
	s_waitcnt vmcnt(7)
	s_nop 0
	v_cndmask_b32_e32 v35, 0, v35, vcc
	v_cndmask_b32_e32 v34, 0, v34, vcc
	v_cndmask_b32_e32 v33, 0, v33, vcc
	v_cndmask_b32_e32 v32, 0, v32, vcc
	v_add_u32_e32 v206, s18, v142
	v_cmp_gt_u32_e32 vcc, s15, v206
	s_waitcnt vmcnt(6)
	s_nop 0
	v_cndmask_b32_e32 v39, 0, v39, vcc
	v_cndmask_b32_e32 v38, 0, v38, vcc
	v_cndmask_b32_e32 v37, 0, v37, vcc
	v_cndmask_b32_e32 v36, 0, v36, vcc
	v_add_u32_e32 v206, s18, v143
	v_cmp_gt_u32_e32 vcc, s15, v206
	s_waitcnt vmcnt(5)
	s_nop 0
	v_cndmask_b32_e32 v43, 0, v43, vcc
	v_cndmask_b32_e32 v42, 0, v42, vcc
	v_cndmask_b32_e32 v41, 0, v41, vcc
	v_cndmask_b32_e32 v40, 0, v40, vcc
	v_add_u32_e32 v206, s18, v144
	v_cmp_gt_u32_e32 vcc, s15, v206
	s_waitcnt vmcnt(4)
	s_nop 0
	v_cndmask_b32_e32 v47, 0, v47, vcc
	v_cndmask_b32_e32 v46, 0, v46, vcc
	v_cndmask_b32_e32 v45, 0, v45, vcc
	v_cndmask_b32_e32 v44, 0, v44, vcc
	v_add_u32_e32 v206, s18, v145
	v_cmp_gt_u32_e32 vcc, s15, v206
	s_waitcnt vmcnt(3)
	s_nop 0
	v_cndmask_b32_e32 v51, 0, v51, vcc
	v_cndmask_b32_e32 v50, 0, v50, vcc
	v_cndmask_b32_e32 v49, 0, v49, vcc
	v_cndmask_b32_e32 v48, 0, v48, vcc
	v_add_u32_e32 v206, s18, v146
	v_cmp_gt_u32_e32 vcc, s15, v206
	s_waitcnt vmcnt(2)
	s_nop 0
	v_cndmask_b32_e32 v55, 0, v55, vcc
	v_cndmask_b32_e32 v54, 0, v54, vcc
	v_cndmask_b32_e32 v53, 0, v53, vcc
	v_cndmask_b32_e32 v52, 0, v52, vcc
	v_add_u32_e32 v206, s18, v147
	v_cmp_gt_u32_e32 vcc, s15, v206
	s_waitcnt vmcnt(1)
	s_nop 0
	v_cndmask_b32_e32 v61, 0, v61, vcc
	v_cndmask_b32_e32 v60, 0, v60, vcc
	v_cndmask_b32_e32 v59, 0, v59, vcc
	v_cndmask_b32_e32 v58, 0, v58, vcc
	v_add_u32_e32 v206, s18, v148
	v_cmp_gt_u32_e32 vcc, s15, v206
	s_waitcnt vmcnt(0)
	s_nop 0
	v_cndmask_b32_e32 v65, 0, v65, vcc
	v_cndmask_b32_e32 v64, 0, v64, vcc
	v_cndmask_b32_e32 v63, 0, v63, vcc
	v_cndmask_b32_e32 v62, 0, v62, vcc
	v_or_b32_e32 v56, s11, v136
	ds_write_b128 v150, v[0:3]
	ds_write_b128 v150, v[4:7] offset:1056
	ds_write_b128 v150, v[8:11] offset:2112
	ds_write_b128 v150, v[12:15] offset:3168
	ds_write_b128 v150, v[16:19] offset:4224
	ds_write_b128 v150, v[20:23] offset:5280
	ds_write_b128 v150, v[24:27] offset:6336
	ds_write_b128 v150, v[28:31] offset:7392
	ds_write_b128 v150, v[32:35] offset:8448
	ds_write_b128 v150, v[36:39] offset:9504
	ds_write_b128 v150, v[40:43] offset:10560
	ds_write_b128 v150, v[44:47] offset:11616
	ds_write_b128 v150, v[48:51] offset:12672
	ds_write_b128 v150, v[52:55] offset:13728
	ds_write_b128 v150, v[58:61] offset:14784
	ds_write_b128 v150, v[62:65] offset:15840
	v_add_u32_e32 v0, s9, v136
	v_ashrrev_i32_e32 v1, 31, v0
	v_lshlrev_b64 v[134:135], 11, v[0:1]
	v_max_i32_e32 v0, 1, v56
	v_min_i32_e32 v1, 0x1fff, v56
	v_sub_u32_e32 v0, v1, v0
	v_add_u32_e32 v0, 2, v0
	v_cvt_f32_i32_e32 v0, v0
	s_waitcnt lgkmcnt(0)
	s_add_i32 s9, s9, s17
	s_cmpk_lt_i32 s0, 0x1000
	v_div_scale_f32 v1, s[18:19], v0, v0, 1.0
	v_rcp_f32_e32 v2, v1
	s_nop 0
	v_fma_f32 v3, -v1, v2, 1.0
	v_fmac_f32_e32 v2, v3, v2
	v_div_scale_f32 v3, vcc, 1.0, v0, 1.0
	v_mul_f32_e32 v4, v3, v2
	v_fma_f32 v5, -v1, v4, v3
	v_fmac_f32_e32 v4, v5, v2
	v_fma_f32 v1, -v1, v4, v3
	v_div_fmas_f32 v1, v1, v2, v4
	v_div_fixup_f32 v20, v1, v0, 1.0
	ds_read_b128 v[0:3], v149 offset:3696
	s_waitcnt lgkmcnt(0)
	v_lshlrev_b32_e32 v4, 16, v0
	v_and_b32_e32 v0, 0xffff0000, v0
	v_lshlrev_b32_e32 v5, 16, v1
	v_and_b32_e32 v1, 0xffff0000, v1
	v_lshlrev_b32_e32 v6, 16, v2
	v_and_b32_e32 v2, 0xffff0000, v2
	v_lshlrev_b32_e32 v7, 16, v3
	v_and_b32_e32 v3, 0xffff0000, v3
	v_add_f32_e32 v8, 0, v0
	v_add_f32_e32 v9, 0, v1
	v_add_f32_e32 v10, 0, v2
	v_add_f32_e32 v11, 0, v3
	ds_read_b128 v[0:3], v149 offset:4224
	v_add_f32_e32 v4, 0, v4
	v_add_f32_e32 v5, 0, v5
	v_add_f32_e32 v6, 0, v6
	v_add_f32_e32 v7, 0, v7
	s_waitcnt lgkmcnt(0)
	v_lshlrev_b32_e32 v12, 16, v0
	v_and_b32_e32 v0, 0xffff0000, v0
	v_lshlrev_b32_e32 v13, 16, v1
	v_and_b32_e32 v1, 0xffff0000, v1
	v_lshlrev_b32_e32 v14, 16, v2
	v_and_b32_e32 v2, 0xffff0000, v2
	v_lshlrev_b32_e32 v15, 16, v3
	v_and_b32_e32 v3, 0xffff0000, v3
	v_add_f32_e32 v8, v8, v0
	v_add_f32_e32 v9, v9, v1
	v_add_f32_e32 v10, v10, v2
	v_add_f32_e32 v11, v11, v3
	v_add_f32_e32 v4, v4, v12
	v_add_f32_e32 v5, v5, v13
	v_add_f32_e32 v6, v6, v14
	v_add_f32_e32 v7, v7, v15
	v_fma_f32 v0, v20, v8, -v0
	v_fma_f32 v1, v20, v9, -v1
	v_fma_f32 v2, v20, v10, -v2
	v_fma_f32 v3, v20, v11, -v3
	v_fma_f32 v4, v20, v4, -v12
	v_fma_f32 v5, v20, v5, -v13
	v_fma_f32 v6, v20, v6, -v14
	v_fma_f32 v7, v20, v7, -v15
	v_cvt_pk_bf16_f32 v0, v4, v0
	v_cvt_pk_bf16_f32 v1, v5, v1
	v_cvt_pk_bf16_f32 v2, v6, v2
	v_cvt_pk_bf16_f32 v3, v7, v3
	s_waitcnt vmcnt(2)
	s_nop 0
	v_mfma_f32_16x16x32_bf16 v[16:19], v[90:93], v[0:3], 0
	s_waitcnt vmcnt(2)
	v_mfma_f32_16x16x32_bf16 v[4:7], v[94:97], v[0:3], 0
	s_waitcnt vmcnt(1)
	v_mfma_f32_16x16x32_bf16 v[8:11], v[106:109], v[0:3], 0
	s_waitcnt vmcnt(0)
	v_mfma_f32_16x16x32_bf16 v[0:3], v[110:113], v[0:3], 0
	global_load_dwordx4 v[90:93], v[86:87], off
	global_load_dwordx4 v[94:97], v[82:83], off
	global_load_dwordx4 v[106:109], v[84:85], off
	global_load_dwordx4 v[110:113], v[88:89], off
	ds_read_b128 v[12:15], v149 offset:3760
	s_waitcnt lgkmcnt(0)
	v_lshlrev_b32_e32 v21, 16, v12
	v_and_b32_e32 v12, 0xffff0000, v12
	v_lshlrev_b32_e32 v22, 16, v13
	v_and_b32_e32 v13, 0xffff0000, v13
	v_lshlrev_b32_e32 v23, 16, v14
	v_and_b32_e32 v14, 0xffff0000, v14
	v_lshlrev_b32_e32 v24, 16, v15
	v_and_b32_e32 v15, 0xffff0000, v15
	v_add_f32_e32 v25, 0, v12
	v_add_f32_e32 v26, 0, v13
	v_add_f32_e32 v27, 0, v14
	v_add_f32_e32 v28, 0, v15
	ds_read_b128 v[12:15], v149 offset:4288
	v_add_f32_e32 v21, 0, v21
	v_add_f32_e32 v22, 0, v22
	v_add_f32_e32 v23, 0, v23
	v_add_f32_e32 v24, 0, v24
	s_waitcnt lgkmcnt(0)
	v_lshlrev_b32_e32 v29, 16, v12
	v_and_b32_e32 v12, 0xffff0000, v12
	v_lshlrev_b32_e32 v30, 16, v13
	v_and_b32_e32 v13, 0xffff0000, v13
	v_lshlrev_b32_e32 v31, 16, v14
	v_and_b32_e32 v14, 0xffff0000, v14
	v_lshlrev_b32_e32 v32, 16, v15
	v_and_b32_e32 v15, 0xffff0000, v15
	v_add_f32_e32 v21, v21, v29
	v_add_f32_e32 v25, v25, v12
	v_add_f32_e32 v22, v22, v30
	v_add_f32_e32 v26, v26, v13
	v_add_f32_e32 v23, v23, v31
	v_add_f32_e32 v27, v27, v14
	v_add_f32_e32 v28, v28, v15
	v_add_f32_e32 v24, v24, v32
	v_fma_f32 v21, v20, v21, -v29
	v_fma_f32 v12, v20, v25, -v12
	v_fma_f32 v22, v20, v22, -v30
	v_fma_f32 v13, v20, v26, -v13
	v_fma_f32 v23, v20, v23, -v31
	v_fma_f32 v14, v20, v27, -v14
	v_fma_f32 v15, v20, v28, -v15
	v_fma_f32 v24, v20, v24, -v32
	v_cvt_pk_bf16_f32 v20, v21, v12
	v_cvt_pk_bf16_f32 v21, v22, v13
	v_cvt_pk_bf16_f32 v22, v23, v14
	v_cvt_pk_bf16_f32 v23, v24, v15
	s_waitcnt vmcnt(0)
	s_nop 0
	v_mfma_f32_16x16x32_bf16 v[12:15], v[166:169], v[20:23], v[4:7]
	s_nop 2
	s_waitcnt vmcnt(0)
	v_mfma_f32_16x16x32_bf16 v[8:11], v[170:173], v[20:23], v[8:11]
	s_waitcnt vmcnt(0)
	v_mfma_f32_16x16x32_bf16 v[4:7], v[174:177], v[20:23], v[16:19]
	s_nop 2
	s_waitcnt vmcnt(0)
	v_mfma_f32_16x16x32_bf16 v[0:3], v[178:181], v[20:23], v[0:3]
	v_max_i32_e32 v16, 2, v56
	v_min_i32_e32 v17, 0x1ffe, v56
	v_sub_u32_e32 v16, v17, v16
	v_add_u32_e32 v16, 4, v16
	v_cvt_f32_i32_e32 v16, v16
	v_div_scale_f32 v17, s[18:19], v16, v16, 1.0
	v_rcp_f32_e32 v18, v17
	s_nop 0
	v_fma_f32 v19, -v17, v18, 1.0
	v_fmac_f32_e32 v18, v19, v18
	v_div_scale_f32 v19, vcc, 1.0, v16, 1.0
	v_mul_f32_e32 v20, v19, v18
	v_fma_f32 v21, -v17, v20, v19
	v_fmac_f32_e32 v20, v21, v18
	v_fma_f32 v17, -v17, v20, v19
	v_div_fmas_f32 v17, v17, v18, v20
	v_div_fixup_f32 v36, v17, v16, 1.0
	ds_read_b128 v[16:19], v149 offset:3296
	s_waitcnt lgkmcnt(0)
	v_lshlrev_b32_e32 v20, 16, v16
	v_and_b32_e32 v16, 0xffff0000, v16
	v_lshlrev_b32_e32 v21, 16, v17
	v_and_b32_e32 v17, 0xffff0000, v17
	v_lshlrev_b32_e32 v22, 16, v18
	v_and_b32_e32 v18, 0xffff0000, v18
	v_lshlrev_b32_e32 v23, 16, v19
	v_and_b32_e32 v19, 0xffff0000, v19
	v_add_f32_e32 v24, 0, v16
	v_add_f32_e32 v25, 0, v17
	v_add_f32_e32 v26, 0, v18
	v_add_f32_e32 v27, 0, v19
	ds_read_b128 v[16:19], v149 offset:3824
	v_add_f32_e32 v20, 0, v20
	v_add_f32_e32 v21, 0, v21
	v_add_f32_e32 v22, 0, v22
	v_add_f32_e32 v23, 0, v23
	s_waitcnt lgkmcnt(0)
	v_lshlrev_b32_e32 v28, 16, v16
	v_and_b32_e32 v16, 0xffff0000, v16
	v_lshlrev_b32_e32 v29, 16, v17
	v_and_b32_e32 v17, 0xffff0000, v17
	v_lshlrev_b32_e32 v30, 16, v18
	v_and_b32_e32 v18, 0xffff0000, v18
	v_lshlrev_b32_e32 v31, 16, v19
	v_and_b32_e32 v19, 0xffff0000, v19
	v_add_f32_e32 v24, v24, v16
	v_add_f32_e32 v25, v25, v17
	v_add_f32_e32 v26, v26, v18
	v_add_f32_e32 v27, v27, v19
	ds_read_b128 v[16:19], v149 offset:4352
	v_add_f32_e32 v20, v20, v28
	v_add_f32_e32 v21, v21, v29
	v_add_f32_e32 v22, v22, v30
	v_add_f32_e32 v23, v23, v31
	s_waitcnt lgkmcnt(0)
	v_lshlrev_b32_e32 v28, 16, v16
	v_and_b32_e32 v29, 0xffff0000, v16
	v_lshlrev_b32_e32 v30, 16, v17
	v_and_b32_e32 v31, 0xffff0000, v17
	v_lshlrev_b32_e32 v32, 16, v18
	v_and_b32_e32 v33, 0xffff0000, v18
	v_lshlrev_b32_e32 v34, 16, v19
	v_and_b32_e32 v35, 0xffff0000, v19
	ds_read_b128 v[16:19], v149 offset:4880
	v_add_f32_e32 v24, v24, v29
	v_add_f32_e32 v25, v25, v31
	v_add_f32_e32 v26, v26, v33
	v_add_f32_e32 v27, v27, v35
	s_waitcnt lgkmcnt(0)
	v_lshlrev_b32_e32 v37, 16, v16
	v_and_b32_e32 v16, 0xffff0000, v16
	v_lshlrev_b32_e32 v38, 16, v17
	v_and_b32_e32 v17, 0xffff0000, v17
	v_lshlrev_b32_e32 v39, 16, v18
	v_and_b32_e32 v18, 0xffff0000, v18
	v_lshlrev_b32_e32 v40, 16, v19
	v_and_b32_e32 v19, 0xffff0000, v19
	v_add_f32_e32 v20, v20, v28
	v_add_f32_e32 v21, v21, v30
	v_add_f32_e32 v22, v22, v32
	v_add_f32_e32 v23, v23, v34
	v_add_f32_e32 v16, v24, v16
	v_add_f32_e32 v17, v25, v17
	v_add_f32_e32 v18, v26, v18
	v_add_f32_e32 v19, v27, v19
	v_add_f32_e32 v20, v20, v37
	v_add_f32_e32 v21, v21, v38
	v_add_f32_e32 v22, v22, v39
	v_add_f32_e32 v23, v23, v40
	v_fma_f32 v16, v36, v16, -v29
	v_fma_f32 v17, v36, v17, -v31
	v_fma_f32 v18, v36, v18, -v33
	v_fma_f32 v19, v36, v19, -v35
	v_fma_f32 v20, v36, v20, -v28
	v_fma_f32 v21, v36, v21, -v30
	v_fma_f32 v22, v36, v22, -v32
	v_fma_f32 v23, v36, v23, -v34
	v_cvt_pk_bf16_f32 v16, v20, v16
	v_cvt_pk_bf16_f32 v17, v21, v17
	v_cvt_pk_bf16_f32 v18, v22, v18
	v_cvt_pk_bf16_f32 v19, v23, v19
	s_waitcnt vmcnt(2)
	s_nop 0
	v_mfma_f32_16x16x32_bf16 v[32:35], v[90:93], v[16:19], 0
	s_waitcnt vmcnt(2)
	v_mfma_f32_16x16x32_bf16 v[20:23], v[94:97], v[16:19], 0
	s_waitcnt vmcnt(1)
	v_mfma_f32_16x16x32_bf16 v[24:27], v[106:109], v[16:19], 0
	s_waitcnt vmcnt(0)
	v_mfma_f32_16x16x32_bf16 v[16:19], v[110:113], v[16:19], 0
	global_load_dwordx4 v[90:93], v[98:99], off
	global_load_dwordx4 v[94:97], v[100:101], off
	global_load_dwordx4 v[106:109], v[102:103], off
	global_load_dwordx4 v[110:113], v[104:105], off
	ds_read_b128 v[28:31], v149 offset:3360
	s_waitcnt lgkmcnt(0)
	v_lshlrev_b32_e32 v37, 16, v28
	v_and_b32_e32 v28, 0xffff0000, v28
	v_lshlrev_b32_e32 v38, 16, v29
	v_and_b32_e32 v29, 0xffff0000, v29
	v_lshlrev_b32_e32 v39, 16, v30
	v_and_b32_e32 v30, 0xffff0000, v30
	v_lshlrev_b32_e32 v40, 16, v31
	v_and_b32_e32 v31, 0xffff0000, v31
	v_add_f32_e32 v41, 0, v28
	v_add_f32_e32 v42, 0, v29
	v_add_f32_e32 v43, 0, v30
	v_add_f32_e32 v44, 0, v31
	ds_read_b128 v[28:31], v149 offset:3888
	v_add_f32_e32 v37, 0, v37
	v_add_f32_e32 v38, 0, v38
	v_add_f32_e32 v39, 0, v39
	v_add_f32_e32 v40, 0, v40
	s_waitcnt lgkmcnt(0)
	v_lshlrev_b32_e32 v45, 16, v28
	v_and_b32_e32 v28, 0xffff0000, v28
	v_lshlrev_b32_e32 v46, 16, v29
	v_and_b32_e32 v29, 0xffff0000, v29
	v_lshlrev_b32_e32 v47, 16, v30
	v_and_b32_e32 v30, 0xffff0000, v30
	v_lshlrev_b32_e32 v48, 16, v31
	v_and_b32_e32 v31, 0xffff0000, v31
	v_add_f32_e32 v41, v41, v28
	v_add_f32_e32 v42, v42, v29
	v_add_f32_e32 v43, v43, v30
	v_add_f32_e32 v44, v44, v31
	ds_read_b128 v[28:31], v149 offset:4416
	v_add_f32_e32 v37, v37, v45
	v_add_f32_e32 v38, v38, v46
	v_add_f32_e32 v39, v39, v47
	v_add_f32_e32 v40, v40, v48
	s_waitcnt lgkmcnt(0)
	v_lshlrev_b32_e32 v45, 16, v28
	v_and_b32_e32 v46, 0xffff0000, v28
	v_lshlrev_b32_e32 v47, 16, v29
	v_and_b32_e32 v48, 0xffff0000, v29
	v_lshlrev_b32_e32 v49, 16, v30
	v_and_b32_e32 v50, 0xffff0000, v30
	v_lshlrev_b32_e32 v51, 16, v31
	v_and_b32_e32 v52, 0xffff0000, v31
	ds_read_b128 v[28:31], v149 offset:4944
	v_add_f32_e32 v37, v37, v45
	v_add_f32_e32 v41, v41, v46
	v_add_f32_e32 v38, v38, v47
	v_add_f32_e32 v42, v42, v48
	v_add_f32_e32 v39, v39, v49
	v_add_f32_e32 v43, v43, v50
	v_add_f32_e32 v44, v44, v52
	s_waitcnt lgkmcnt(0)
	v_lshlrev_b32_e32 v53, 16, v28
	v_and_b32_e32 v28, 0xffff0000, v28
	v_lshlrev_b32_e32 v54, 16, v29
	v_and_b32_e32 v29, 0xffff0000, v29
	v_lshlrev_b32_e32 v55, 16, v30
	v_and_b32_e32 v30, 0xffff0000, v30
	v_lshlrev_b32_e32 v57, 16, v31
	v_and_b32_e32 v31, 0xffff0000, v31
	v_add_f32_e32 v40, v40, v51
	v_add_f32_e32 v37, v37, v53
	v_add_f32_e32 v28, v41, v28
	v_add_f32_e32 v38, v38, v54
	v_add_f32_e32 v29, v42, v29
	v_add_f32_e32 v39, v39, v55
	v_add_f32_e32 v30, v43, v30
	v_add_f32_e32 v31, v44, v31
	v_add_f32_e32 v40, v40, v57
	v_fma_f32 v37, v36, v37, -v45
	v_fma_f32 v28, v36, v28, -v46
	v_fma_f32 v38, v36, v38, -v47
	v_fma_f32 v29, v36, v29, -v48
	v_fma_f32 v39, v36, v39, -v49
	v_fma_f32 v30, v36, v30, -v50
	v_fma_f32 v31, v36, v31, -v52
	v_fma_f32 v40, v36, v40, -v51
	v_cvt_pk_bf16_f32 v36, v37, v28
	v_cvt_pk_bf16_f32 v37, v38, v29
	v_cvt_pk_bf16_f32 v38, v39, v30
	v_cvt_pk_bf16_f32 v39, v40, v31
	s_waitcnt vmcnt(0)
	s_nop 0
	v_mfma_f32_16x16x32_bf16 v[28:31], v[182:185], v[36:39], v[20:23]
	s_nop 2
	s_waitcnt vmcnt(0)
	v_mfma_f32_16x16x32_bf16 v[24:27], v[186:189], v[36:39], v[24:27]
	s_waitcnt vmcnt(0)
	v_mfma_f32_16x16x32_bf16 v[20:23], v[190:193], v[36:39], v[32:35]
	s_nop 2
	s_waitcnt vmcnt(0)
	v_mfma_f32_16x16x32_bf16 v[16:19], v[194:197], v[36:39], v[16:19]
	v_max_i32_e32 v32, 4, v56
	v_min_i32_e32 v33, 0x1ffc, v56
	v_sub_u32_e32 v32, v33, v32
	v_add_u32_e32 v32, 8, v32
	v_cvt_f32_i32_e32 v32, v32
	v_div_scale_f32 v33, s[18:19], v32, v32, 1.0
	v_rcp_f32_e32 v34, v33
	s_nop 0
	v_fma_f32 v35, -v33, v34, 1.0
	v_fmac_f32_e32 v34, v35, v34
	v_div_scale_f32 v35, vcc, 1.0, v32, 1.0
	v_mul_f32_e32 v36, v35, v34
	v_fma_f32 v37, -v33, v36, v35
	v_fmac_f32_e32 v36, v37, v34
	v_fma_f32 v33, -v33, v36, v35
	v_div_fmas_f32 v33, v33, v34, v36
	v_div_fixup_f32 v40, v33, v32, 1.0
	ds_read_b128 v[32:35], v149 offset:2368
	s_waitcnt lgkmcnt(0)
	v_lshlrev_b32_e32 v36, 16, v32
	v_and_b32_e32 v32, 0xffff0000, v32
	v_lshlrev_b32_e32 v37, 16, v33
	v_and_b32_e32 v33, 0xffff0000, v33
	v_lshlrev_b32_e32 v38, 16, v34
	v_and_b32_e32 v34, 0xffff0000, v34
	v_lshlrev_b32_e32 v39, 16, v35
	v_and_b32_e32 v35, 0xffff0000, v35
	v_add_f32_e32 v41, 0, v32
	v_add_f32_e32 v42, 0, v33
	v_add_f32_e32 v43, 0, v34
	v_add_f32_e32 v44, 0, v35
	ds_read_b128 v[32:35], v149 offset:2896
	v_add_f32_e32 v36, 0, v36
	v_add_f32_e32 v37, 0, v37
	v_add_f32_e32 v38, 0, v38
	v_add_f32_e32 v39, 0, v39
	s_waitcnt lgkmcnt(0)
	v_lshlrev_b32_e32 v45, 16, v32
	v_and_b32_e32 v32, 0xffff0000, v32
	v_lshlrev_b32_e32 v46, 16, v33
	v_and_b32_e32 v33, 0xffff0000, v33
	v_lshlrev_b32_e32 v47, 16, v34
	v_and_b32_e32 v34, 0xffff0000, v34
	v_lshlrev_b32_e32 v48, 16, v35
	v_and_b32_e32 v35, 0xffff0000, v35
	v_add_f32_e32 v41, v41, v32
	v_add_f32_e32 v42, v42, v33
	v_add_f32_e32 v43, v43, v34
	v_add_f32_e32 v44, v44, v35
	ds_read_b128 v[32:35], v149 offset:3424
	v_add_f32_e32 v36, v36, v45
	v_add_f32_e32 v37, v37, v46
	v_add_f32_e32 v38, v38, v47
	v_add_f32_e32 v39, v39, v48
	s_waitcnt lgkmcnt(0)
	v_lshlrev_b32_e32 v45, 16, v32
	v_and_b32_e32 v32, 0xffff0000, v32
	v_lshlrev_b32_e32 v46, 16, v33
	v_and_b32_e32 v33, 0xffff0000, v33
	v_lshlrev_b32_e32 v47, 16, v34
	v_and_b32_e32 v34, 0xffff0000, v34
	v_lshlrev_b32_e32 v48, 16, v35
	v_and_b32_e32 v35, 0xffff0000, v35
	v_add_f32_e32 v41, v41, v32
	v_add_f32_e32 v42, v42, v33
	v_add_f32_e32 v43, v43, v34
	v_add_f32_e32 v44, v44, v35
	ds_read_b128 v[32:35], v149 offset:3952
	v_add_f32_e32 v36, v36, v45
	v_add_f32_e32 v37, v37, v46
	v_add_f32_e32 v38, v38, v47
	v_add_f32_e32 v39, v39, v48
	s_waitcnt lgkmcnt(0)
	v_lshlrev_b32_e32 v45, 16, v32
	v_lshlrev_b32_e32 v46, 16, v33
	v_lshlrev_b32_e32 v47, 16, v34
	v_lshlrev_b32_e32 v48, 16, v35
	v_add_f32_e32 v45, v36, v45
	v_add_f32_e32 v46, v37, v46
	v_add_f32_e32 v47, v38, v47
	v_add_f32_e32 v48, v39, v48
	ds_read_b128 v[36:39], v149 offset:4480
	v_and_b32_e32 v32, 0xffff0000, v32
	v_and_b32_e32 v33, 0xffff0000, v33
	v_and_b32_e32 v34, 0xffff0000, v34
	v_and_b32_e32 v35, 0xffff0000, v35
	v_add_f32_e32 v41, v41, v32
	v_add_f32_e32 v42, v42, v33
	v_add_f32_e32 v43, v43, v34
	v_add_f32_e32 v44, v44, v35
	s_waitcnt lgkmcnt(0)
	v_lshlrev_b32_e32 v32, 16, v36
	v_and_b32_e32 v33, 0xffff0000, v36
	v_lshlrev_b32_e32 v34, 16, v37
	v_and_b32_e32 v35, 0xffff0000, v37
	v_lshlrev_b32_e32 v36, 16, v38
	v_and_b32_e32 v37, 0xffff0000, v38
	v_lshlrev_b32_e32 v38, 16, v39
	v_and_b32_e32 v39, 0xffff0000, v39
	v_add_f32_e32 v49, v45, v32
	v_add_f32_e32 v50, v42, v35
	v_add_f32_e32 v51, v43, v37
	v_add_f32_e32 v52, v44, v39
	ds_read_b128 v[42:45], v149 offset:5008
	v_add_f32_e32 v41, v41, v33
	v_add_f32_e32 v46, v46, v34
	v_add_f32_e32 v47, v47, v36
	v_add_f32_e32 v48, v48, v38
	s_waitcnt lgkmcnt(0)
	v_lshlrev_b32_e32 v53, 16, v42
	v_and_b32_e32 v42, 0xffff0000, v42
	v_lshlrev_b32_e32 v54, 16, v43
	v_and_b32_e32 v43, 0xffff0000, v43
	v_lshlrev_b32_e32 v55, 16, v44
	v_and_b32_e32 v44, 0xffff0000, v44
	v_lshlrev_b32_e32 v57, 16, v45
	v_and_b32_e32 v45, 0xffff0000, v45
	v_add_f32_e32 v49, v49, v53
	v_add_f32_e32 v53, v41, v42
	v_add_f32_e32 v50, v50, v43
	v_add_f32_e32 v51, v51, v44
	v_add_f32_e32 v52, v52, v45
	ds_read_b128 v[42:45], v149 offset:5536
	v_add_f32_e32 v46, v46, v54
	v_add_f32_e32 v47, v47, v55
	v_add_f32_e32 v48, v48, v57
	s_waitcnt lgkmcnt(0)
	v_lshlrev_b32_e32 v41, 16, v42
	v_and_b32_e32 v42, 0xffff0000, v42
	v_lshlrev_b32_e32 v54, 16, v43
	v_and_b32_e32 v55, 0xffff0000, v43
	v_lshlrev_b32_e32 v57, 16, v44
	v_and_b32_e32 v58, 0xffff0000, v44
	v_lshlrev_b32_e32 v59, 16, v45
	v_and_b32_e32 v60, 0xffff0000, v45
	v_add_f32_e32 v42, v53, v42
	v_add_f32_e32 v43, v46, v54
	v_add_f32_e32 v44, v50, v55
	v_add_f32_e32 v45, v47, v57
	v_add_f32_e32 v46, v51, v58
	v_add_f32_e32 v47, v48, v59
	v_add_f32_e32 v48, v52, v60
	ds_read_b128 v[50:53], v149 offset:6064
	v_add_f32_e32 v41, v49, v41
	s_waitcnt lgkmcnt(0)
	v_lshlrev_b32_e32 v49, 16, v50
	v_and_b32_e32 v50, 0xffff0000, v50
	v_lshlrev_b32_e32 v54, 16, v51
	v_and_b32_e32 v51, 0xffff0000, v51
	v_lshlrev_b32_e32 v55, 16, v52
	v_and_b32_e32 v52, 0xffff0000, v52
	v_lshlrev_b32_e32 v57, 16, v53
	v_and_b32_e32 v53, 0xffff0000, v53
	v_add_f32_e32 v41, v41, v49
	v_add_f32_e32 v42, v42, v50
	v_add_f32_e32 v43, v43, v54
	v_add_f32_e32 v44, v44, v51
	v_add_f32_e32 v45, v45, v55
	v_add_f32_e32 v46, v46, v52
	v_add_f32_e32 v47, v47, v57
	v_add_f32_e32 v48, v48, v53
	v_fma_f32 v32, v40, v41, -v32
	v_fma_f32 v33, v40, v42, -v33
	v_fma_f32 v34, v40, v43, -v34
	v_fma_f32 v35, v40, v44, -v35
	v_fma_f32 v36, v40, v45, -v36
	v_fma_f32 v37, v40, v46, -v37
	v_fma_f32 v38, v40, v47, -v38
	v_fma_f32 v39, v40, v48, -v39
	v_cvt_pk_bf16_f32 v42, v32, v33
	v_cvt_pk_bf16_f32 v43, v34, v35
	v_cvt_pk_bf16_f32 v44, v36, v37
	v_cvt_pk_bf16_f32 v45, v38, v39
	s_waitcnt vmcnt(3)
	s_nop 0
	v_mfma_f32_16x16x32_bf16 v[32:35], v[90:93], v[42:45], 0
	s_waitcnt vmcnt(2)
	v_mfma_f32_16x16x32_bf16 v[36:39], v[94:97], v[42:45], 0
	s_waitcnt vmcnt(1)
	v_mfma_f32_16x16x32_bf16 v[48:51], v[106:109], v[42:45], 0
	s_waitcnt vmcnt(0)
	v_mfma_f32_16x16x32_bf16 v[52:55], v[110:113], v[42:45], 0
	global_load_dwordx4 v[90:93], v[114:115], off
	global_load_dwordx4 v[94:97], v[116:117], off
	global_load_dwordx4 v[106:109], v[118:119], off
	global_load_dwordx4 v[110:113], v[120:121], off
	ds_read_b128 v[42:45], v149 offset:2432
	s_waitcnt lgkmcnt(0)
	v_lshlrev_b32_e32 v41, 16, v42
	v_and_b32_e32 v42, 0xffff0000, v42
	v_lshlrev_b32_e32 v46, 16, v43
	v_and_b32_e32 v43, 0xffff0000, v43
	v_lshlrev_b32_e32 v47, 16, v44
	v_and_b32_e32 v44, 0xffff0000, v44
	v_lshlrev_b32_e32 v57, 16, v45
	v_and_b32_e32 v45, 0xffff0000, v45
	v_add_f32_e32 v58, 0, v42
	v_add_f32_e32 v59, 0, v43
	v_add_f32_e32 v60, 0, v44
	v_add_f32_e32 v61, 0, v45
	ds_read_b128 v[42:45], v149 offset:2960
	v_add_f32_e32 v41, 0, v41
	v_add_f32_e32 v46, 0, v46
	v_add_f32_e32 v47, 0, v47
	v_add_f32_e32 v57, 0, v57
	s_waitcnt lgkmcnt(0)
	v_lshlrev_b32_e32 v62, 16, v42
	v_and_b32_e32 v42, 0xffff0000, v42
	v_lshlrev_b32_e32 v63, 16, v43
	v_and_b32_e32 v43, 0xffff0000, v43
	v_lshlrev_b32_e32 v64, 16, v44
	v_and_b32_e32 v44, 0xffff0000, v44
	v_lshlrev_b32_e32 v65, 16, v45
	v_and_b32_e32 v45, 0xffff0000, v45
	v_add_f32_e32 v58, v58, v42
	v_add_f32_e32 v59, v59, v43
	v_add_f32_e32 v60, v60, v44
	v_add_f32_e32 v61, v61, v45
	ds_read_b128 v[42:45], v149 offset:3488
	v_add_f32_e32 v41, v41, v62
	v_add_f32_e32 v46, v46, v63
	v_add_f32_e32 v47, v47, v64
	v_add_f32_e32 v57, v57, v65
	s_waitcnt lgkmcnt(0)
	v_lshlrev_b32_e32 v62, 16, v42
	v_and_b32_e32 v42, 0xffff0000, v42
	v_lshlrev_b32_e32 v63, 16, v43
	v_and_b32_e32 v43, 0xffff0000, v43
	v_lshlrev_b32_e32 v64, 16, v44
	v_and_b32_e32 v44, 0xffff0000, v44
	v_lshlrev_b32_e32 v65, 16, v45
	v_and_b32_e32 v45, 0xffff0000, v45
	v_add_f32_e32 v58, v58, v42
	v_add_f32_e32 v59, v59, v43
	v_add_f32_e32 v60, v60, v44
	v_add_f32_e32 v61, v61, v45
	ds_read_b128 v[42:45], v149 offset:4016
	v_add_f32_e32 v41, v41, v62
	v_add_f32_e32 v46, v46, v63
	v_add_f32_e32 v47, v47, v64
	v_add_f32_e32 v57, v57, v65
	s_waitcnt lgkmcnt(0)
	v_lshlrev_b32_e32 v62, 16, v42
	v_and_b32_e32 v42, 0xffff0000, v42
	v_lshlrev_b32_e32 v63, 16, v43
	v_and_b32_e32 v43, 0xffff0000, v43
	v_lshlrev_b32_e32 v64, 16, v44
	v_and_b32_e32 v44, 0xffff0000, v44
	v_lshlrev_b32_e32 v65, 16, v45
	v_and_b32_e32 v45, 0xffff0000, v45
	v_add_f32_e32 v66, v58, v42
	v_add_f32_e32 v67, v59, v43
	v_add_f32_e32 v68, v60, v44
	v_add_f32_e32 v69, v61, v45
	ds_read_b128 v[58:61], v149 offset:4544
	v_add_f32_e32 v62, v41, v62
	v_add_f32_e32 v63, v46, v63
	v_add_f32_e32 v64, v47, v64
	v_add_f32_e32 v65, v57, v65
	s_waitcnt lgkmcnt(0)
	v_lshlrev_b32_e32 v41, 16, v58
	v_and_b32_e32 v42, 0xffff0000, v58
	v_lshlrev_b32_e32 v43, 16, v59
	v_and_b32_e32 v44, 0xffff0000, v59
	v_lshlrev_b32_e32 v45, 16, v60
	v_and_b32_e32 v46, 0xffff0000, v60
	v_lshlrev_b32_e32 v47, 16, v61
	v_and_b32_e32 v57, 0xffff0000, v61
	ds_read_b128 v[58:61], v149 offset:5072
	v_add_f32_e32 v66, v66, v42
	v_add_f32_e32 v67, v67, v44
	v_add_f32_e32 v68, v68, v46
	v_add_f32_e32 v69, v69, v57
	s_waitcnt lgkmcnt(0)
	v_lshlrev_b32_e32 v70, 16, v58
	v_and_b32_e32 v58, 0xffff0000, v58
	v_lshlrev_b32_e32 v71, 16, v59
	v_and_b32_e32 v59, 0xffff0000, v59
	v_lshlrev_b32_e32 v131, 16, v60
	v_and_b32_e32 v60, 0xffff0000, v60
	v_lshlrev_b32_e32 v133, 16, v61
	v_and_b32_e32 v61, 0xffff0000, v61
	v_add_f32_e32 v66, v66, v58
	v_add_f32_e32 v67, v67, v59
	v_add_f32_e32 v68, v68, v60
	v_add_f32_e32 v69, v69, v61
	ds_read_b128 v[58:61], v149 offset:5600
	v_add_f32_e32 v62, v62, v41
	v_add_f32_e32 v63, v63, v43
	v_add_f32_e32 v64, v64, v45
	v_add_f32_e32 v65, v65, v47
	v_add_f32_e32 v62, v62, v70
	v_add_f32_e32 v63, v63, v71
	v_add_f32_e32 v64, v64, v131
	v_add_f32_e32 v65, v65, v133
	s_waitcnt lgkmcnt(0)
	v_lshlrev_b32_e32 v70, 16, v58
	v_and_b32_e32 v71, 0xffff0000, v58
	v_lshlrev_b32_e32 v131, 16, v59
	v_and_b32_e32 v133, 0xffff0000, v59
	v_lshlrev_b32_e32 v151, 16, v60
	v_and_b32_e32 v152, 0xffff0000, v60
	v_lshlrev_b32_e32 v153, 16, v61
	v_and_b32_e32 v154, 0xffff0000, v61
	v_add_f32_e32 v58, v62, v70
	v_add_f32_e32 v59, v66, v71
	v_add_f32_e32 v60, v63, v131
	v_add_f32_e32 v61, v67, v133
	v_add_f32_e32 v62, v64, v151
	v_add_f32_e32 v63, v68, v152
	v_add_f32_e32 v64, v65, v153
	v_add_f32_e32 v65, v69, v154
	ds_read_b128 v[66:69], v149 offset:6128
	s_waitcnt lgkmcnt(0)
	v_lshlrev_b32_e32 v70, 16, v66
	v_and_b32_e32 v66, 0xffff0000, v66
	v_lshlrev_b32_e32 v71, 16, v67
	v_and_b32_e32 v67, 0xffff0000, v67
	v_lshlrev_b32_e32 v131, 16, v68
	v_and_b32_e32 v68, 0xffff0000, v68
	v_lshlrev_b32_e32 v133, 16, v69
	v_and_b32_e32 v69, 0xffff0000, v69
	v_add_f32_e32 v58, v58, v70
	v_add_f32_e32 v59, v59, v66
	v_add_f32_e32 v60, v60, v71
	v_add_f32_e32 v61, v61, v67
	v_add_f32_e32 v62, v62, v131
	v_add_f32_e32 v63, v63, v68
	v_add_f32_e32 v64, v64, v133
	v_add_f32_e32 v65, v65, v69
	v_fma_f32 v41, v40, v58, -v41
	v_fma_f32 v42, v40, v59, -v42
	v_fma_f32 v43, v40, v60, -v43
	v_fma_f32 v44, v40, v61, -v44
	v_fma_f32 v45, v40, v62, -v45
	v_fma_f32 v46, v40, v63, -v46
	v_fma_f32 v47, v40, v64, -v47
	v_fma_f32 v40, v40, v65, -v57
	v_cvt_pk_bf16_f32 v58, v41, v42
	v_cvt_pk_bf16_f32 v59, v43, v44
	v_cvt_pk_bf16_f32 v60, v45, v46
	v_cvt_pk_bf16_f32 v61, v47, v40
	s_waitcnt vmcnt(0)
	s_nop 0
	v_mfma_f32_16x16x32_bf16 v[44:47], v[198:201], v[58:61], v[32:35]
	s_nop 2
	s_waitcnt vmcnt(0)
	v_mfma_f32_16x16x32_bf16 v[40:43], v[202:205], v[58:61], v[36:39]
	s_waitcnt vmcnt(0)
	v_mfma_f32_16x16x32_bf16 v[36:39], v[214:217], v[58:61], v[48:51]
	s_nop 1
	v_max_i32_e32 v48, 8, v56
	v_min_i32_e32 v49, 0x1ff8, v56
	v_sub_u32_e32 v48, v49, v48
	v_add_u32_e32 v48, 16, v48
	v_cvt_f32_i32_e32 v48, v48
	s_waitcnt vmcnt(0)
	v_mfma_f32_16x16x32_bf16 v[32:35], v[218:221], v[58:61], v[52:55]
	v_div_scale_f32 v49, s[18:19], v48, v48, 1.0
	v_rcp_f32_e32 v50, v49
	s_mov_b64 s[18:19], 0x1a000200
	v_fma_f32 v51, -v49, v50, 1.0
	v_fmac_f32_e32 v50, v51, v50
	v_div_scale_f32 v51, vcc, 1.0, v48, 1.0
	v_mul_f32_e32 v52, v51, v50
	v_fma_f32 v53, -v49, v52, v51
	v_fmac_f32_e32 v52, v53, v50
	v_fma_f32 v49, -v49, v52, v51
	v_div_fmas_f32 v49, v49, v50, v52
	v_div_fixup_f32 v56, v49, v48, 1.0
	ds_read_b128 v[48:51], v149 offset:384
	s_waitcnt lgkmcnt(0)
	v_lshlrev_b32_e32 v52, 16, v48
	v_and_b32_e32 v48, 0xffff0000, v48
	v_lshlrev_b32_e32 v53, 16, v49
	v_and_b32_e32 v49, 0xffff0000, v49
	v_lshlrev_b32_e32 v54, 16, v50
	v_and_b32_e32 v50, 0xffff0000, v50
	v_lshlrev_b32_e32 v55, 16, v51
	v_and_b32_e32 v51, 0xffff0000, v51
	v_add_f32_e32 v57, 0, v48
	v_add_f32_e32 v58, 0, v49
	v_add_f32_e32 v59, 0, v50
	v_add_f32_e32 v60, 0, v51
	ds_read_b128 v[48:51], v149 offset:912
	v_add_f32_e32 v52, 0, v52
	v_add_f32_e32 v53, 0, v53
	v_add_f32_e32 v54, 0, v54
	v_add_f32_e32 v55, 0, v55
	s_waitcnt lgkmcnt(0)
	v_lshlrev_b32_e32 v61, 16, v48
	v_and_b32_e32 v48, 0xffff0000, v48
	v_lshlrev_b32_e32 v62, 16, v49
	v_and_b32_e32 v49, 0xffff0000, v49
	v_lshlrev_b32_e32 v63, 16, v50
	v_and_b32_e32 v50, 0xffff0000, v50
	v_lshlrev_b32_e32 v64, 16, v51
	v_and_b32_e32 v51, 0xffff0000, v51
	v_add_f32_e32 v57, v57, v48
	v_add_f32_e32 v58, v58, v49
	v_add_f32_e32 v59, v59, v50
	v_add_f32_e32 v60, v60, v51
	ds_read_b128 v[48:51], v149 offset:1440
	v_add_f32_e32 v52, v52, v61
	v_add_f32_e32 v53, v53, v62
	v_add_f32_e32 v54, v54, v63
	v_add_f32_e32 v55, v55, v64
	s_waitcnt lgkmcnt(0)
	v_lshlrev_b32_e32 v61, 16, v48
	v_and_b32_e32 v48, 0xffff0000, v48
	v_lshlrev_b32_e32 v62, 16, v49
	v_and_b32_e32 v49, 0xffff0000, v49
	v_lshlrev_b32_e32 v63, 16, v50
	v_and_b32_e32 v50, 0xffff0000, v50
	v_lshlrev_b32_e32 v64, 16, v51
	v_and_b32_e32 v51, 0xffff0000, v51
	v_add_f32_e32 v57, v57, v48
	v_add_f32_e32 v58, v58, v49
	v_add_f32_e32 v59, v59, v50
	v_add_f32_e32 v60, v60, v51
	ds_read_b128 v[48:51], v149 offset:1968
	v_add_f32_e32 v52, v52, v61
	v_add_f32_e32 v53, v53, v62
	v_add_f32_e32 v54, v54, v63
	v_add_f32_e32 v55, v55, v64
	s_waitcnt lgkmcnt(0)
	v_lshlrev_b32_e32 v61, 16, v48
	v_and_b32_e32 v48, 0xffff0000, v48
	v_lshlrev_b32_e32 v62, 16, v49
	v_and_b32_e32 v49, 0xffff0000, v49
	v_lshlrev_b32_e32 v63, 16, v50
	v_and_b32_e32 v50, 0xffff0000, v50
	v_lshlrev_b32_e32 v64, 16, v51
	v_and_b32_e32 v51, 0xffff0000, v51
	v_add_f32_e32 v57, v57, v48
	v_add_f32_e32 v58, v58, v49
	v_add_f32_e32 v59, v59, v50
	v_add_f32_e32 v60, v60, v51
	ds_read_b128 v[48:51], v149 offset:2496
	v_add_f32_e32 v52, v52, v61
	v_add_f32_e32 v53, v53, v62
	v_add_f32_e32 v54, v54, v63
	v_add_f32_e32 v55, v55, v64
	s_waitcnt lgkmcnt(0)
	v_lshlrev_b32_e32 v61, 16, v48
	v_and_b32_e32 v48, 0xffff0000, v48
	v_lshlrev_b32_e32 v62, 16, v49
	v_and_b32_e32 v49, 0xffff0000, v49
	v_lshlrev_b32_e32 v63, 16, v50
	v_and_b32_e32 v50, 0xffff0000, v50
	v_lshlrev_b32_e32 v64, 16, v51
	v_and_b32_e32 v51, 0xffff0000, v51
	v_add_f32_e32 v57, v57, v48
	v_add_f32_e32 v58, v58, v49
	v_add_f32_e32 v59, v59, v50
	v_add_f32_e32 v60, v60, v51
	ds_read_b128 v[48:51], v149 offset:3024
	v_add_f32_e32 v52, v52, v61
	v_add_f32_e32 v53, v53, v62
	v_add_f32_e32 v54, v54, v63
	v_add_f32_e32 v55, v55, v64
	s_waitcnt lgkmcnt(0)
	v_lshlrev_b32_e32 v61, 16, v48
	v_and_b32_e32 v48, 0xffff0000, v48
	v_lshlrev_b32_e32 v62, 16, v49
	v_and_b32_e32 v49, 0xffff0000, v49
	v_lshlrev_b32_e32 v63, 16, v50
	v_and_b32_e32 v50, 0xffff0000, v50
	v_lshlrev_b32_e32 v64, 16, v51
	v_and_b32_e32 v51, 0xffff0000, v51
	v_add_f32_e32 v57, v57, v48
	v_add_f32_e32 v58, v58, v49
	v_add_f32_e32 v59, v59, v50
	v_add_f32_e32 v60, v60, v51
	ds_read_b128 v[48:51], v149 offset:3552
	v_add_f32_e32 v52, v52, v61
	v_add_f32_e32 v53, v53, v62
	v_add_f32_e32 v54, v54, v63
	v_add_f32_e32 v55, v55, v64
	s_waitcnt lgkmcnt(0)
	v_lshlrev_b32_e32 v61, 16, v48
	v_and_b32_e32 v48, 0xffff0000, v48
	v_lshlrev_b32_e32 v62, 16, v49
	v_and_b32_e32 v49, 0xffff0000, v49
	v_lshlrev_b32_e32 v63, 16, v50
	v_and_b32_e32 v50, 0xffff0000, v50
	v_lshlrev_b32_e32 v64, 16, v51
	v_and_b32_e32 v51, 0xffff0000, v51
	v_add_f32_e32 v57, v57, v48
	v_add_f32_e32 v58, v58, v49
	v_add_f32_e32 v59, v59, v50
	v_add_f32_e32 v60, v60, v51
	ds_read_b128 v[48:51], v149 offset:4080
	v_add_f32_e32 v52, v52, v61
	v_add_f32_e32 v53, v53, v62
	v_add_f32_e32 v54, v54, v63
	v_add_f32_e32 v55, v55, v64
	s_waitcnt lgkmcnt(0)
	v_lshlrev_b32_e32 v61, 16, v48
	v_lshlrev_b32_e32 v62, 16, v49
	v_lshlrev_b32_e32 v63, 16, v50
	v_lshlrev_b32_e32 v64, 16, v51
	v_add_f32_e32 v61, v52, v61
	v_add_f32_e32 v62, v53, v62
	v_add_f32_e32 v63, v54, v63
	v_add_f32_e32 v64, v55, v64
	ds_read_b128 v[52:55], v149 offset:4608
	v_and_b32_e32 v48, 0xffff0000, v48
	v_and_b32_e32 v49, 0xffff0000, v49
	v_and_b32_e32 v50, 0xffff0000, v50
	v_and_b32_e32 v51, 0xffff0000, v51
	v_add_f32_e32 v57, v57, v48
	v_add_f32_e32 v58, v58, v49
	v_add_f32_e32 v59, v59, v50
	v_add_f32_e32 v60, v60, v51
	s_waitcnt lgkmcnt(0)
	v_lshlrev_b32_e32 v48, 16, v52
	v_and_b32_e32 v49, 0xffff0000, v52
	v_lshlrev_b32_e32 v50, 16, v53
	v_and_b32_e32 v51, 0xffff0000, v53
	v_lshlrev_b32_e32 v52, 16, v54
	v_and_b32_e32 v53, 0xffff0000, v54
	v_lshlrev_b32_e32 v54, 16, v55
	v_and_b32_e32 v55, 0xffff0000, v55
	v_add_f32_e32 v65, v61, v48
	v_add_f32_e32 v66, v58, v51
	v_add_f32_e32 v67, v59, v53
	v_add_f32_e32 v68, v60, v55
	ds_read_b128 v[58:61], v149 offset:5136
	v_add_f32_e32 v57, v57, v49
	v_add_f32_e32 v62, v62, v50
	v_add_f32_e32 v63, v63, v52
	v_add_f32_e32 v64, v64, v54
	s_waitcnt lgkmcnt(0)
	v_lshlrev_b32_e32 v69, 16, v58
	v_and_b32_e32 v58, 0xffff0000, v58
	v_lshlrev_b32_e32 v70, 16, v59
	v_and_b32_e32 v59, 0xffff0000, v59
	v_lshlrev_b32_e32 v71, 16, v60
	v_and_b32_e32 v60, 0xffff0000, v60
	v_lshlrev_b32_e32 v131, 16, v61
	v_and_b32_e32 v61, 0xffff0000, v61
	v_add_f32_e32 v57, v57, v58
	v_add_f32_e32 v66, v66, v59
	v_add_f32_e32 v67, v67, v60
	v_add_f32_e32 v68, v68, v61
	ds_read_b128 v[58:61], v149 offset:5664
	v_add_f32_e32 v65, v65, v69
	v_add_f32_e32 v62, v62, v70
	v_add_f32_e32 v63, v63, v71
	v_add_f32_e32 v64, v64, v131
	s_waitcnt lgkmcnt(0)
	v_lshlrev_b32_e32 v69, 16, v58
	v_and_b32_e32 v58, 0xffff0000, v58
	v_lshlrev_b32_e32 v70, 16, v59
	v_and_b32_e32 v59, 0xffff0000, v59
	v_lshlrev_b32_e32 v71, 16, v60
	v_and_b32_e32 v60, 0xffff0000, v60
	v_lshlrev_b32_e32 v131, 16, v61
	v_and_b32_e32 v61, 0xffff0000, v61
	v_add_f32_e32 v57, v57, v58
	v_add_f32_e32 v66, v66, v59
	v_add_f32_e32 v67, v67, v60
	v_add_f32_e32 v68, v68, v61
	ds_read_b128 v[58:61], v149 offset:6192
	v_add_f32_e32 v65, v65, v69
	v_add_f32_e32 v62, v62, v70
	v_add_f32_e32 v63, v63, v71
	v_add_f32_e32 v64, v64, v131
	s_waitcnt lgkmcnt(0)
	v_lshlrev_b32_e32 v69, 16, v58
	v_and_b32_e32 v58, 0xffff0000, v58
	v_lshlrev_b32_e32 v70, 16, v59
	v_and_b32_e32 v59, 0xffff0000, v59
	v_lshlrev_b32_e32 v71, 16, v60
	v_and_b32_e32 v60, 0xffff0000, v60
	v_lshlrev_b32_e32 v131, 16, v61
	v_and_b32_e32 v61, 0xffff0000, v61
	v_add_f32_e32 v57, v57, v58
	v_add_f32_e32 v66, v66, v59
	v_add_f32_e32 v67, v67, v60
	v_add_f32_e32 v68, v68, v61
	ds_read_b128 v[58:61], v149 offset:6720
	v_add_f32_e32 v65, v65, v69
	v_add_f32_e32 v62, v62, v70
	v_add_f32_e32 v63, v63, v71
	v_add_f32_e32 v64, v64, v131
	s_waitcnt lgkmcnt(0)
	v_lshlrev_b32_e32 v69, 16, v58
	v_and_b32_e32 v58, 0xffff0000, v58
	v_lshlrev_b32_e32 v70, 16, v59
	v_and_b32_e32 v59, 0xffff0000, v59
	v_lshlrev_b32_e32 v71, 16, v60
	v_and_b32_e32 v60, 0xffff0000, v60
	v_lshlrev_b32_e32 v131, 16, v61
	v_and_b32_e32 v61, 0xffff0000, v61
	v_add_f32_e32 v57, v57, v58
	v_add_f32_e32 v66, v66, v59
	v_add_f32_e32 v67, v67, v60
	v_add_f32_e32 v68, v68, v61
	ds_read_b128 v[58:61], v149 offset:7248
	v_add_f32_e32 v65, v65, v69
	v_add_f32_e32 v62, v62, v70
	v_add_f32_e32 v63, v63, v71
	v_add_f32_e32 v64, v64, v131
	s_waitcnt lgkmcnt(0)
	v_lshlrev_b32_e32 v69, 16, v58
	v_and_b32_e32 v58, 0xffff0000, v58
	v_lshlrev_b32_e32 v70, 16, v59
	v_and_b32_e32 v59, 0xffff0000, v59
	v_lshlrev_b32_e32 v71, 16, v60
	v_and_b32_e32 v60, 0xffff0000, v60
	v_lshlrev_b32_e32 v131, 16, v61
	v_and_b32_e32 v61, 0xffff0000, v61
	v_add_f32_e32 v65, v65, v69
	v_add_f32_e32 v69, v57, v58
	v_add_f32_e32 v66, v66, v59
	v_add_f32_e32 v67, v67, v60
	v_add_f32_e32 v68, v68, v61
	ds_read_b128 v[58:61], v149 offset:7776
	v_add_f32_e32 v63, v63, v71
	v_add_f32_e32 v64, v64, v131
	v_add_f32_e32 v62, v62, v70
	s_waitcnt lgkmcnt(0)
	v_lshlrev_b32_e32 v131, 16, v60
	v_lshlrev_b32_e32 v151, 16, v61
	v_and_b32_e32 v152, 0xffff0000, v61
	v_add_f32_e32 v61, v63, v131
	v_add_f32_e32 v63, v64, v151
	v_add_f32_e32 v64, v68, v152
	ds_read_b128 v[152:155], v149 offset:8304
	v_lshlrev_b32_e32 v57, 16, v58
	v_and_b32_e32 v58, 0xffff0000, v58
	v_lshlrev_b32_e32 v70, 16, v59
	v_and_b32_e32 v71, 0xffff0000, v59
	v_and_b32_e32 v133, 0xffff0000, v60
	v_add_f32_e32 v57, v65, v57
	v_add_f32_e32 v58, v69, v58
	v_add_f32_e32 v59, v62, v70
	v_add_f32_e32 v60, v66, v71
	v_add_f32_e32 v62, v67, v133
	s_waitcnt lgkmcnt(0)
	v_lshlrev_b32_e32 v65, 16, v152
	v_and_b32_e32 v66, 0xffff0000, v152
	v_lshlrev_b32_e32 v67, 16, v153
	v_and_b32_e32 v68, 0xffff0000, v153
	v_lshlrev_b32_e32 v69, 16, v154
	v_and_b32_e32 v70, 0xffff0000, v154
	v_lshlrev_b32_e32 v71, 16, v155
	v_and_b32_e32 v131, 0xffff0000, v155
	v_add_f32_e32 v57, v57, v65
	v_add_f32_e32 v58, v58, v66
	v_add_f32_e32 v59, v59, v67
	v_add_f32_e32 v60, v60, v68
	v_add_f32_e32 v61, v61, v69
	v_add_f32_e32 v62, v62, v70
	v_add_f32_e32 v63, v63, v71
	v_add_f32_e32 v64, v64, v131
	v_fma_f32 v48, v56, v57, -v48
	v_fma_f32 v49, v56, v58, -v49
	v_fma_f32 v50, v56, v59, -v50
	v_fma_f32 v51, v56, v60, -v51
	v_fma_f32 v52, v56, v61, -v52
	v_fma_f32 v53, v56, v62, -v53
	v_fma_f32 v54, v56, v63, -v54
	v_fma_f32 v55, v56, v64, -v55
	v_cvt_pk_bf16_f32 v58, v48, v49
	v_cvt_pk_bf16_f32 v59, v50, v51
	v_cvt_pk_bf16_f32 v60, v52, v53
	v_cvt_pk_bf16_f32 v61, v54, v55
	s_waitcnt vmcnt(3)
	s_nop 0
	v_mfma_f32_16x16x32_bf16 v[48:51], v[90:93], v[58:61], 0
	s_waitcnt vmcnt(2)
	v_mfma_f32_16x16x32_bf16 v[52:55], v[94:97], v[58:61], 0
	s_waitcnt vmcnt(1)
	v_mfma_f32_16x16x32_bf16 v[64:67], v[106:109], v[58:61], 0
	s_waitcnt vmcnt(0)
	v_mfma_f32_16x16x32_bf16 v[68:71], v[110:113], v[58:61], 0
	ds_read_b128 v[58:61], v149 offset:448
	s_waitcnt lgkmcnt(0)
	v_lshlrev_b32_e32 v57, 16, v58
	v_and_b32_e32 v58, 0xffff0000, v58
	v_lshlrev_b32_e32 v62, 16, v59
	v_and_b32_e32 v59, 0xffff0000, v59
	v_lshlrev_b32_e32 v63, 16, v60
	v_and_b32_e32 v60, 0xffff0000, v60
	v_lshlrev_b32_e32 v131, 16, v61
	v_and_b32_e32 v61, 0xffff0000, v61
	v_add_f32_e32 v133, 0, v58
	v_add_f32_e32 v151, 0, v59
	v_add_f32_e32 v152, 0, v60
	v_add_f32_e32 v153, 0, v61
	ds_read_b128 v[58:61], v149 offset:976
	v_add_f32_e32 v57, 0, v57
	v_add_f32_e32 v62, 0, v62
	v_add_f32_e32 v63, 0, v63
	v_add_f32_e32 v131, 0, v131
	s_waitcnt lgkmcnt(0)
	v_lshlrev_b32_e32 v154, 16, v58
	v_and_b32_e32 v58, 0xffff0000, v58
	v_lshlrev_b32_e32 v155, 16, v59
	v_and_b32_e32 v59, 0xffff0000, v59
	v_lshlrev_b32_e32 v156, 16, v60
	v_and_b32_e32 v60, 0xffff0000, v60
	v_lshlrev_b32_e32 v157, 16, v61
	v_and_b32_e32 v61, 0xffff0000, v61
	v_add_f32_e32 v133, v133, v58
	v_add_f32_e32 v151, v151, v59
	v_add_f32_e32 v152, v152, v60
	v_add_f32_e32 v153, v153, v61
	ds_read_b128 v[58:61], v149 offset:1504
	v_add_f32_e32 v57, v57, v154
	v_add_f32_e32 v62, v62, v155
	v_add_f32_e32 v63, v63, v156
	v_add_f32_e32 v131, v131, v157
	s_waitcnt lgkmcnt(0)
	v_lshlrev_b32_e32 v154, 16, v58
	v_and_b32_e32 v58, 0xffff0000, v58
	v_lshlrev_b32_e32 v155, 16, v59
	v_and_b32_e32 v59, 0xffff0000, v59
	v_lshlrev_b32_e32 v156, 16, v60
	v_and_b32_e32 v60, 0xffff0000, v60
	v_lshlrev_b32_e32 v157, 16, v61
	v_and_b32_e32 v61, 0xffff0000, v61
	v_add_f32_e32 v133, v133, v58
	v_add_f32_e32 v151, v151, v59
	v_add_f32_e32 v152, v152, v60
	v_add_f32_e32 v153, v153, v61
	ds_read_b128 v[58:61], v149 offset:2032
	v_add_f32_e32 v57, v57, v154
	v_add_f32_e32 v62, v62, v155
	v_add_f32_e32 v63, v63, v156
	v_add_f32_e32 v131, v131, v157
	s_waitcnt lgkmcnt(0)
	v_lshlrev_b32_e32 v154, 16, v58
	v_and_b32_e32 v58, 0xffff0000, v58
	v_lshlrev_b32_e32 v155, 16, v59
	v_and_b32_e32 v59, 0xffff0000, v59
	v_lshlrev_b32_e32 v156, 16, v60
	v_and_b32_e32 v60, 0xffff0000, v60
	v_lshlrev_b32_e32 v157, 16, v61
	v_and_b32_e32 v61, 0xffff0000, v61
	v_add_f32_e32 v133, v133, v58
	v_add_f32_e32 v151, v151, v59
	v_add_f32_e32 v152, v152, v60
	v_add_f32_e32 v153, v153, v61
	ds_read_b128 v[58:61], v149 offset:2560
	v_add_f32_e32 v57, v57, v154
	v_add_f32_e32 v62, v62, v155
	v_add_f32_e32 v63, v63, v156
	v_add_f32_e32 v131, v131, v157
	s_waitcnt lgkmcnt(0)
	v_lshlrev_b32_e32 v154, 16, v58
	v_and_b32_e32 v58, 0xffff0000, v58
	v_lshlrev_b32_e32 v155, 16, v59
	v_and_b32_e32 v59, 0xffff0000, v59
	v_lshlrev_b32_e32 v156, 16, v60
	v_and_b32_e32 v60, 0xffff0000, v60
	v_lshlrev_b32_e32 v157, 16, v61
	v_and_b32_e32 v61, 0xffff0000, v61
	v_add_f32_e32 v133, v133, v58
	v_add_f32_e32 v151, v151, v59
	v_add_f32_e32 v152, v152, v60
	v_add_f32_e32 v153, v153, v61
	ds_read_b128 v[58:61], v149 offset:3088
	v_add_f32_e32 v57, v57, v154
	v_add_f32_e32 v62, v62, v155
	v_add_f32_e32 v63, v63, v156
	v_add_f32_e32 v131, v131, v157
	s_waitcnt lgkmcnt(0)
	v_lshlrev_b32_e32 v154, 16, v58
	v_and_b32_e32 v58, 0xffff0000, v58
	v_lshlrev_b32_e32 v155, 16, v59
	v_and_b32_e32 v59, 0xffff0000, v59
	v_lshlrev_b32_e32 v156, 16, v60
	v_and_b32_e32 v60, 0xffff0000, v60
	v_lshlrev_b32_e32 v157, 16, v61
	v_and_b32_e32 v61, 0xffff0000, v61
	v_add_f32_e32 v133, v133, v58
	v_add_f32_e32 v151, v151, v59
	v_add_f32_e32 v152, v152, v60
	v_add_f32_e32 v153, v153, v61
	ds_read_b128 v[58:61], v149 offset:3616
	v_add_f32_e32 v57, v57, v154
	v_add_f32_e32 v62, v62, v155
	v_add_f32_e32 v63, v63, v156
	v_add_f32_e32 v131, v131, v157
	s_waitcnt lgkmcnt(0)
	v_lshlrev_b32_e32 v154, 16, v58
	v_and_b32_e32 v58, 0xffff0000, v58
	v_lshlrev_b32_e32 v155, 16, v59
	v_and_b32_e32 v59, 0xffff0000, v59
	v_lshlrev_b32_e32 v156, 16, v60
	v_and_b32_e32 v60, 0xffff0000, v60
	v_lshlrev_b32_e32 v157, 16, v61
	v_and_b32_e32 v61, 0xffff0000, v61
	v_add_f32_e32 v133, v133, v58
	v_add_f32_e32 v151, v151, v59
	v_add_f32_e32 v152, v152, v60
	v_add_f32_e32 v153, v153, v61
	ds_read_b128 v[58:61], v149 offset:4144
	v_add_f32_e32 v57, v57, v154
	v_add_f32_e32 v62, v62, v155
	v_add_f32_e32 v63, v63, v156
	v_add_f32_e32 v131, v131, v157
	s_waitcnt lgkmcnt(0)
	v_lshlrev_b32_e32 v154, 16, v58
	v_lshlrev_b32_e32 v155, 16, v59
	v_lshlrev_b32_e32 v156, 16, v60
	v_and_b32_e32 v60, 0xffff0000, v60
	v_lshlrev_b32_e32 v157, 16, v61
	v_and_b32_e32 v61, 0xffff0000, v61
	v_add_f32_e32 v158, v57, v154
	v_add_f32_e32 v159, v62, v155
	v_add_f32_e32 v160, v152, v60
	v_add_f32_e32 v161, v153, v61
	ds_read_b128 v[152:155], v149 offset:4672
	v_and_b32_e32 v58, 0xffff0000, v58
	v_and_b32_e32 v59, 0xffff0000, v59
	v_add_f32_e32 v133, v133, v58
	v_add_f32_e32 v151, v151, v59
	v_add_f32_e32 v156, v63, v156
	v_add_f32_e32 v157, v131, v157
	s_waitcnt lgkmcnt(0)
	v_lshlrev_b32_e32 v57, 16, v152
	v_and_b32_e32 v58, 0xffff0000, v152
	v_lshlrev_b32_e32 v59, 16, v153
	v_and_b32_e32 v60, 0xffff0000, v153
	v_lshlrev_b32_e32 v61, 16, v154
	v_and_b32_e32 v62, 0xffff0000, v154
	v_lshlrev_b32_e32 v63, 16, v155
	v_and_b32_e32 v131, 0xffff0000, v155
	ds_read_b128 v[152:155], v149 offset:5200
	v_add_f32_e32 v133, v133, v58
	v_add_f32_e32 v151, v151, v60
	v_add_f32_e32 v160, v160, v62
	v_add_f32_e32 v161, v161, v131
	s_waitcnt lgkmcnt(0)
	v_lshlrev_b32_e32 v162, 16, v152
	v_and_b32_e32 v152, 0xffff0000, v152
	v_lshlrev_b32_e32 v163, 16, v153
	v_and_b32_e32 v153, 0xffff0000, v153
	v_lshlrev_b32_e32 v164, 16, v154
	v_and_b32_e32 v154, 0xffff0000, v154
	v_lshlrev_b32_e32 v165, 16, v155
	v_and_b32_e32 v155, 0xffff0000, v155
	v_add_f32_e32 v133, v133, v152
	v_add_f32_e32 v151, v151, v153
	v_add_f32_e32 v160, v160, v154
	v_add_f32_e32 v161, v161, v155
	ds_read_b128 v[152:155], v149 offset:5728
	v_add_f32_e32 v158, v158, v57
	v_add_f32_e32 v159, v159, v59
	v_add_f32_e32 v156, v156, v61
	v_add_f32_e32 v157, v157, v63
	v_add_f32_e32 v158, v158, v162
	v_add_f32_e32 v159, v159, v163
	v_add_f32_e32 v156, v156, v164
	v_add_f32_e32 v157, v157, v165
	s_waitcnt lgkmcnt(0)
	v_lshlrev_b32_e32 v162, 16, v152
	v_and_b32_e32 v152, 0xffff0000, v152
	v_lshlrev_b32_e32 v163, 16, v153
	v_and_b32_e32 v153, 0xffff0000, v153
	v_lshlrev_b32_e32 v164, 16, v154
	v_and_b32_e32 v154, 0xffff0000, v154
	v_lshlrev_b32_e32 v165, 16, v155
	v_and_b32_e32 v155, 0xffff0000, v155
	v_add_f32_e32 v133, v133, v152
	v_add_f32_e32 v151, v151, v153
	v_add_f32_e32 v160, v160, v154
	v_add_f32_e32 v161, v161, v155
	ds_read_b128 v[152:155], v149 offset:6256
	v_add_f32_e32 v158, v158, v162
	v_add_f32_e32 v159, v159, v163
	v_add_f32_e32 v156, v156, v164
	v_add_f32_e32 v157, v157, v165
	s_waitcnt lgkmcnt(0)
	v_lshlrev_b32_e32 v162, 16, v152
	v_and_b32_e32 v152, 0xffff0000, v152
	v_lshlrev_b32_e32 v163, 16, v153
	v_and_b32_e32 v153, 0xffff0000, v153
	v_lshlrev_b32_e32 v164, 16, v154
	v_and_b32_e32 v154, 0xffff0000, v154
	v_lshlrev_b32_e32 v165, 16, v155
	v_and_b32_e32 v155, 0xffff0000, v155
	v_add_f32_e32 v133, v133, v152
	v_add_f32_e32 v151, v151, v153
	v_add_f32_e32 v160, v160, v154
	v_add_f32_e32 v161, v161, v155
	ds_read_b128 v[152:155], v149 offset:6784
	v_add_f32_e32 v158, v158, v162
	v_add_f32_e32 v159, v159, v163
	v_add_f32_e32 v156, v156, v164
	v_add_f32_e32 v157, v157, v165
	s_waitcnt lgkmcnt(0)
	v_lshlrev_b32_e32 v162, 16, v152
	v_and_b32_e32 v152, 0xffff0000, v152
	v_lshlrev_b32_e32 v163, 16, v153
	v_and_b32_e32 v153, 0xffff0000, v153
	v_lshlrev_b32_e32 v164, 16, v154
	v_and_b32_e32 v154, 0xffff0000, v154
	v_lshlrev_b32_e32 v165, 16, v155
	v_and_b32_e32 v155, 0xffff0000, v155
	v_add_f32_e32 v133, v133, v152
	v_add_f32_e32 v151, v151, v153
	v_add_f32_e32 v160, v160, v154
	v_add_f32_e32 v161, v161, v155
	ds_read_b128 v[152:155], v149 offset:7312
	v_add_f32_e32 v158, v158, v162
	v_add_f32_e32 v159, v159, v163
	v_add_f32_e32 v156, v156, v164
	v_add_f32_e32 v157, v157, v165
	s_waitcnt lgkmcnt(0)
	v_lshlrev_b32_e32 v162, 16, v152
	v_and_b32_e32 v152, 0xffff0000, v152
	v_lshlrev_b32_e32 v163, 16, v153
	v_and_b32_e32 v153, 0xffff0000, v153
	v_lshlrev_b32_e32 v164, 16, v154
	v_and_b32_e32 v154, 0xffff0000, v154
	v_lshlrev_b32_e32 v165, 16, v155
	v_and_b32_e32 v155, 0xffff0000, v155
	v_add_f32_e32 v133, v133, v152
	v_add_f32_e32 v151, v151, v153
	v_add_f32_e32 v160, v160, v154
	v_add_f32_e32 v161, v161, v155
	ds_read_b128 v[152:155], v149 offset:7840
	v_add_f32_e32 v158, v158, v162
	v_add_f32_e32 v159, v159, v163
	v_add_f32_e32 v156, v156, v164
	v_add_f32_e32 v157, v157, v165
	s_waitcnt lgkmcnt(0)
	v_lshlrev_b32_e32 v162, 16, v152
	v_and_b32_e32 v152, 0xffff0000, v152
	v_lshlrev_b32_e32 v163, 16, v153
	v_and_b32_e32 v153, 0xffff0000, v153
	v_lshlrev_b32_e32 v164, 16, v154
	v_and_b32_e32 v154, 0xffff0000, v154
	v_lshlrev_b32_e32 v165, 16, v155
	v_and_b32_e32 v155, 0xffff0000, v155
	v_add_f32_e32 v133, v133, v152
	v_add_f32_e32 v151, v151, v153
	v_add_f32_e32 v160, v160, v154
	v_add_f32_e32 v161, v161, v155
	ds_read_b128 v[152:155], v149 offset:8368
	v_add_f32_e32 v158, v158, v162
	v_add_f32_e32 v159, v159, v163
	v_add_f32_e32 v156, v156, v164
	v_add_f32_e32 v157, v157, v165
	s_waitcnt lgkmcnt(0)
	v_lshlrev_b32_e32 v162, 16, v152
	v_and_b32_e32 v152, 0xffff0000, v152
	v_lshlrev_b32_e32 v163, 16, v153
	v_and_b32_e32 v153, 0xffff0000, v153
	v_lshlrev_b32_e32 v164, 16, v154
	v_and_b32_e32 v154, 0xffff0000, v154
	v_lshlrev_b32_e32 v165, 16, v155
	v_and_b32_e32 v155, 0xffff0000, v155
	v_add_f32_e32 v158, v158, v162
	v_add_f32_e32 v133, v133, v152
	v_add_f32_e32 v152, v159, v163
	v_add_f32_e32 v151, v151, v153
	v_add_f32_e32 v153, v156, v164
	v_add_f32_e32 v154, v160, v154
	v_add_f32_e32 v156, v157, v165
	v_add_f32_e32 v155, v161, v155
	v_fma_f32 v57, v56, v158, -v57
	v_fma_f32 v58, v56, v133, -v58
	v_fma_f32 v59, v56, v152, -v59
	v_fma_f32 v60, v56, v151, -v60
	v_fma_f32 v61, v56, v153, -v61
	v_fma_f32 v62, v56, v154, -v62
	v_fma_f32 v63, v56, v156, -v63
	v_fma_f32 v56, v56, v155, -v131
	v_cvt_pk_bf16_f32 v152, v57, v58
	v_cvt_pk_bf16_f32 v153, v59, v60
	v_cvt_pk_bf16_f32 v154, v61, v62
	v_cvt_pk_bf16_f32 v155, v63, v56
	s_waitcnt vmcnt(0)
	s_nop 0
	v_mfma_f32_16x16x32_bf16 v[60:63], v[222:225], v[152:155], v[48:51]
	s_nop 2
	v_mov_b32_e32 v133, v209
	s_waitcnt vmcnt(0)
	v_mfma_f32_16x16x32_bf16 v[56:59], v[226:229], v[152:155], v[52:55]
	s_waitcnt vmcnt(0)
	v_mfma_f32_16x16x32_bf16 v[52:55], v[230:233], v[152:155], v[64:67]
	s_nop 1
	v_pk_mul_f32 v[64:65], v[14:15], v[14:15]
	v_pk_mul_f32 v[66:67], v[12:13], v[12:13]
	s_waitcnt vmcnt(0)
	v_mfma_f32_16x16x32_bf16 v[48:51], v[234:237], v[152:155], v[68:71]
	s_nop 2
	v_pk_mov_b32 v[68:69], v[66:67], v[64:65] op_sel:[1,0]
	v_mov_b32_e32 v67, v65
	v_pk_add_f32 v[64:65], v[68:69], v[66:67]
	v_pk_mul_f32 v[66:67], v[10:11], v[10:11]
	v_pk_mul_f32 v[68:69], v[8:9], v[8:9]
	v_pk_add_f32 v[64:65], v[64:65], v[64:65] op_sel:[0,1] op_sel_hi:[1,0]
	v_pk_mov_b32 v[70:71], v[68:69], v[66:67] op_sel:[1,0]
	v_mov_b32_e32 v69, v67
	v_pk_add_f32 v[66:67], v[70:71], v[68:69]
	v_mul_f32_e32 v68, v0, v0
	v_mul_f32_e32 v69, v1, v1
	v_pk_add_f32 v[66:67], v[66:67], v[66:67] op_sel:[0,1] op_sel_hi:[1,0]
	v_mov_b32_e32 v65, v68
	v_mov_b32_e32 v67, v69
	v_pk_add_f32 v[64:65], v[64:65], v[66:67]
	v_mul_f32_e32 v66, v5, v5
	v_mul_f32_e32 v68, v7, v7
	v_mul_f32_e32 v70, v2, v2
	v_mul_f32_e32 v71, v3, v3
	v_pk_fma_f32 v[66:67], v[4:5], v[4:5], v[66:67] op_sel_hi:[1,1,0]
	v_pk_fma_f32 v[68:69], v[6:7], v[6:7], v[68:69] op_sel_hi:[1,1,0]
	v_mov_b32_e32 v67, v70
	v_mov_b32_e32 v69, v71
	v_pk_add_f32 v[66:67], v[66:67], v[68:69]
	v_pk_mul_f32 v[68:69], v[28:29], v[28:29]
	v_pk_add_f32 v[64:65], v[64:65], v[66:67]
	v_pk_mul_f32 v[66:67], v[30:31], v[30:31]
	v_pk_add_f32 v[64:65], v[64:65], v[64:65] op_sel:[0,1] op_sel_hi:[1,0]
	v_pk_mov_b32 v[70:71], v[68:69], v[66:67] op_sel:[1,0]
	v_mov_b32_e32 v69, v67
	v_pk_add_f32 v[66:67], v[70:71], v[68:69]
	v_mul_f32_e32 v68, v20, v20
	v_mul_f32_e32 v69, v21, v21
	v_pk_add_f32 v[66:67], v[66:67], v[66:67] op_sel:[0,1] op_sel_hi:[1,0]
	v_mov_b32_e32 v65, v68
	v_mov_b32_e32 v67, v69
	v_pk_add_f32 v[64:65], v[64:65], v[66:67]
	v_mul_f32_e32 v66, v25, v25
	v_mul_f32_e32 v68, v27, v27
	v_mul_f32_e32 v70, v22, v22
	v_mul_f32_e32 v71, v23, v23
	v_pk_fma_f32 v[66:67], v[24:25], v[24:25], v[66:67] op_sel_hi:[1,1,0]
	v_pk_fma_f32 v[68:69], v[26:27], v[26:27], v[68:69] op_sel_hi:[1,1,0]
	v_mov_b32_e32 v67, v70
	v_mov_b32_e32 v69, v71
	v_pk_add_f32 v[66:67], v[66:67], v[68:69]
	v_pk_mul_f32 v[68:69], v[16:17], v[16:17]
	v_pk_add_f32 v[64:65], v[64:65], v[66:67]
	v_pk_mul_f32 v[66:67], v[18:19], v[18:19]
	v_pk_add_f32 v[64:65], v[64:65], v[64:65] op_sel:[0,1] op_sel_hi:[1,0]
	v_pk_mov_b32 v[70:71], v[68:69], v[66:67] op_sel:[1,0]
	v_mov_b32_e32 v69, v67
	v_pk_add_f32 v[66:67], v[70:71], v[68:69]
	v_mul_f32_e32 v68, v40, v40
	v_mul_f32_e32 v69, v41, v41
	v_pk_add_f32 v[66:67], v[66:67], v[66:67] op_sel:[0,1] op_sel_hi:[1,0]
	v_mov_b32_e32 v65, v68
	v_mov_b32_e32 v67, v69
	v_pk_add_f32 v[64:65], v[64:65], v[66:67]
	v_mul_f32_e32 v66, v45, v45
	v_mul_f32_e32 v68, v47, v47
	v_mul_f32_e32 v70, v42, v42
	v_mul_f32_e32 v71, v43, v43
	v_pk_fma_f32 v[66:67], v[44:45], v[44:45], v[66:67] op_sel_hi:[1,1,0]
	v_pk_fma_f32 v[68:69], v[46:47], v[46:47], v[68:69] op_sel_hi:[1,1,0]
	v_mov_b32_e32 v67, v70
	v_mov_b32_e32 v69, v71
	v_pk_add_f32 v[66:67], v[66:67], v[68:69]
	v_pk_mul_f32 v[68:69], v[36:37], v[36:37]
	v_pk_add_f32 v[64:65], v[64:65], v[66:67]
	v_pk_mul_f32 v[66:67], v[38:39], v[38:39]
	v_pk_add_f32 v[64:65], v[64:65], v[64:65] op_sel:[0,1] op_sel_hi:[1,0]
	v_pk_mov_b32 v[70:71], v[68:69], v[66:67] op_sel:[1,0]
	v_mov_b32_e32 v69, v67
	v_pk_add_f32 v[66:67], v[70:71], v[68:69]
	v_mul_f32_e32 v68, v60, v60
	v_mul_f32_e32 v69, v61, v61
	v_pk_add_f32 v[66:67], v[66:67], v[66:67] op_sel:[0,1] op_sel_hi:[1,0]
	v_mov_b32_e32 v65, v68
	v_mov_b32_e32 v67, v69
	v_pk_add_f32 v[64:65], v[64:65], v[66:67]
	v_mul_f32_e32 v66, v33, v33
	v_mul_f32_e32 v68, v35, v35
	v_mul_f32_e32 v70, v62, v62
	v_mul_f32_e32 v71, v63, v63
	v_pk_fma_f32 v[66:67], v[32:33], v[32:33], v[66:67] op_sel_hi:[1,1,0]
	v_pk_fma_f32 v[68:69], v[34:35], v[34:35], v[68:69] op_sel_hi:[1,1,0]
	v_mov_b32_e32 v67, v70
	v_mov_b32_e32 v69, v71
	v_pk_add_f32 v[66:67], v[66:67], v[68:69]
	v_pk_mul_f32 v[68:69], v[56:57], v[56:57]
	v_pk_add_f32 v[64:65], v[64:65], v[66:67]
	v_pk_mul_f32 v[66:67], v[58:59], v[58:59]
	v_pk_add_f32 v[64:65], v[64:65], v[64:65] op_sel:[0,1] op_sel_hi:[1,0]
	v_pk_mov_b32 v[70:71], v[68:69], v[66:67] op_sel:[1,0]
	v_mov_b32_e32 v69, v67
	v_pk_add_f32 v[66:67], v[70:71], v[68:69]
	v_mul_f32_e32 v68, v48, v48
	v_mul_f32_e32 v69, v49, v49
	v_pk_add_f32 v[66:67], v[66:67], v[66:67] op_sel:[0,1] op_sel_hi:[1,0]
	v_mov_b32_e32 v65, v68
	v_mov_b32_e32 v67, v69
	v_pk_add_f32 v[64:65], v[64:65], v[66:67]
	v_mul_f32_e32 v66, v53, v53
	v_mul_f32_e32 v68, v55, v55
	v_mul_f32_e32 v70, v50, v50
	v_mul_f32_e32 v71, v51, v51
	v_pk_fma_f32 v[66:67], v[52:53], v[52:53], v[66:67] op_sel_hi:[1,1,0]
	v_pk_fma_f32 v[68:69], v[54:55], v[54:55], v[68:69] op_sel_hi:[1,1,0]
	v_mov_b32_e32 v67, v70
	v_mov_b32_e32 v69, v71
	v_pk_add_f32 v[66:67], v[66:67], v[68:69]
	v_and_b32_e32 v68, 64, v245
	v_pk_add_f32 v[64:65], v[64:65], v[66:67]
	v_xor_b32_e32 v67, 16, v245
	v_add_u32_e32 v68, 64, v68
	v_cmp_lt_i32_e32 vcc, v67, v68
	v_add_f32_e32 v66, v64, v65
	v_lshl_add_u64 v[64:65], s[84:85], 0, v[134:135]
	v_cndmask_b32_e32 v67, v245, v67, vcc
	v_lshlrev_b32_e32 v67, 2, v67
	ds_bpermute_b32 v67, v67, v66
	v_lshl_add_u64 v[64:65], v[64:65], 0, v[132:133]
	s_waitcnt lgkmcnt(0)
	v_add_f32_e32 v66, v66, v67
	v_xor_b32_e32 v67, 32, v245
	v_cmp_lt_i32_e32 vcc, v67, v68
	v_lshl_add_u64 v[68:69], v[64:65], 0, s[18:19]
	s_nop 0
	v_cndmask_b32_e32 v67, v245, v67, vcc
	v_lshlrev_b32_e32 v67, 2, v67
	ds_bpermute_b32 v67, v67, v66
	s_waitcnt lgkmcnt(0)
	v_add_f32_e32 v66, v66, v67
	v_fmamk_f32 v66, v66, 0x3b800000, v244
	v_cmp_gt_f32_e32 vcc, s7, v66
	v_mul_f32_e32 v67, 0x4b800000, v66
	s_nop 0
	v_cndmask_b32_e32 v66, v66, v67, vcc
	v_rsq_f32_e32 v66, v66
	s_nop 0
	v_mul_f32_e32 v67, 0x45800000, v66
	v_cndmask_b32_e32 v66, v66, v67, vcc
	v_mbcnt_lo_u32_b32 v78, -1, 0
	v_mbcnt_hi_u32_b32 v78, -1, v78
	v_lshrrev_b32_e32 v78, 4, v78
	v_and_b32_e32 v78, 1, v78
	v_mul_u32_u24_e32 v78, 24, v78
	v_mov_b32_e32 v79, v209
	v_lshl_add_u64 v[80:81], v[68:69], 0, v[78:79]
	v_mul_f32_e32 v12, v12, v66
	v_mul_f32_e32 v13, v13, v66
	v_cvt_pk_bf16_f32 v122, v12, v13
	v_mul_f32_e32 v14, v14, v66
	v_mul_f32_e32 v15, v15, v66
	v_cvt_pk_bf16_f32 v123, v14, v15
	v_mul_f32_e32 v8, v8, v66
	v_mul_f32_e32 v9, v9, v66
	v_cvt_pk_bf16_f32 v124, v8, v9
	v_mul_f32_e32 v10, v10, v66
	v_mul_f32_e32 v11, v11, v66
	v_cvt_pk_bf16_f32 v125, v10, v11
	s_nop 1
	v_permlane16_swap_b32_e32 v122, v124
	v_permlane16_swap_b32_e32 v123, v125
	global_store_dwordx4 v[80:81], v[122:125], off
	v_mul_f32_e32 v4, v4, v66
	v_mul_f32_e32 v5, v5, v66
	v_cvt_pk_bf16_f32 v126, v4, v5
	v_mul_f32_e32 v6, v6, v66
	v_mul_f32_e32 v7, v7, v66
	v_cvt_pk_bf16_f32 v127, v6, v7
	v_mul_f32_e32 v0, v0, v66
	v_mul_f32_e32 v1, v1, v66
	v_cvt_pk_bf16_f32 v128, v0, v1
	v_mul_f32_e32 v2, v2, v66
	v_mul_f32_e32 v3, v3, v66
	v_cvt_pk_bf16_f32 v129, v2, v3
	s_nop 1
	v_permlane16_swap_b32_e32 v126, v128
	v_permlane16_swap_b32_e32 v127, v129
	global_store_dwordx4 v[80:81], v[126:129], off offset:64
	v_mul_f32_e32 v28, v28, v66
	v_mul_f32_e32 v29, v29, v66
	v_cvt_pk_bf16_f32 v122, v28, v29
	v_mul_f32_e32 v30, v30, v66
	v_mul_f32_e32 v31, v31, v66
	v_cvt_pk_bf16_f32 v123, v30, v31
	v_mul_f32_e32 v24, v24, v66
	v_mul_f32_e32 v25, v25, v66
	v_cvt_pk_bf16_f32 v124, v24, v25
	v_mul_f32_e32 v26, v26, v66
	v_mul_f32_e32 v27, v27, v66
	v_cvt_pk_bf16_f32 v125, v26, v27
	s_nop 1
	v_permlane16_swap_b32_e32 v122, v124
	v_permlane16_swap_b32_e32 v123, v125
	global_store_dwordx4 v[80:81], v[122:125], off offset:128
	v_mul_f32_e32 v20, v20, v66
	v_mul_f32_e32 v21, v21, v66
	v_cvt_pk_bf16_f32 v126, v20, v21
	v_mul_f32_e32 v22, v22, v66
	v_mul_f32_e32 v23, v23, v66
	v_cvt_pk_bf16_f32 v127, v22, v23
	v_mul_f32_e32 v16, v16, v66
	v_mul_f32_e32 v17, v17, v66
	v_cvt_pk_bf16_f32 v128, v16, v17
	v_mul_f32_e32 v18, v18, v66
	v_mul_f32_e32 v19, v19, v66
	v_cvt_pk_bf16_f32 v129, v18, v19
	s_nop 1
	v_permlane16_swap_b32_e32 v126, v128
	v_permlane16_swap_b32_e32 v127, v129
	global_store_dwordx4 v[80:81], v[126:129], off offset:192
	v_mul_f32_e32 v44, v44, v66
	v_mul_f32_e32 v45, v45, v66
	v_cvt_pk_bf16_f32 v122, v44, v45
	v_mul_f32_e32 v46, v46, v66
	v_mul_f32_e32 v47, v47, v66
	v_cvt_pk_bf16_f32 v123, v46, v47
	v_mul_f32_e32 v40, v40, v66
	v_mul_f32_e32 v41, v41, v66
	v_cvt_pk_bf16_f32 v124, v40, v41
	v_mul_f32_e32 v42, v42, v66
	v_mul_f32_e32 v43, v43, v66
	v_cvt_pk_bf16_f32 v125, v42, v43
	s_nop 1
	v_permlane16_swap_b32_e32 v122, v124
	v_permlane16_swap_b32_e32 v123, v125
	global_store_dwordx4 v[80:81], v[122:125], off offset:256
	v_mul_f32_e32 v36, v36, v66
	v_mul_f32_e32 v37, v37, v66
	v_cvt_pk_bf16_f32 v126, v36, v37
	v_mul_f32_e32 v38, v38, v66
	v_mul_f32_e32 v39, v39, v66
	v_cvt_pk_bf16_f32 v127, v38, v39
	v_mul_f32_e32 v32, v32, v66
	v_mul_f32_e32 v33, v33, v66
	v_cvt_pk_bf16_f32 v128, v32, v33
	v_mul_f32_e32 v34, v34, v66
	v_mul_f32_e32 v35, v35, v66
	v_cvt_pk_bf16_f32 v129, v34, v35
	s_nop 1
	v_permlane16_swap_b32_e32 v126, v128
	v_permlane16_swap_b32_e32 v127, v129
	global_store_dwordx4 v[80:81], v[126:129], off offset:320
	v_mul_f32_e32 v60, v60, v66
	v_mul_f32_e32 v61, v61, v66
	v_cvt_pk_bf16_f32 v122, v60, v61
	v_mul_f32_e32 v62, v62, v66
	v_mul_f32_e32 v63, v63, v66
	v_cvt_pk_bf16_f32 v123, v62, v63
	v_mul_f32_e32 v56, v56, v66
	v_mul_f32_e32 v57, v57, v66
	v_cvt_pk_bf16_f32 v124, v56, v57
	v_mul_f32_e32 v58, v58, v66
	v_mul_f32_e32 v59, v59, v66
	v_cvt_pk_bf16_f32 v125, v58, v59
	s_nop 1
	v_permlane16_swap_b32_e32 v122, v124
	v_permlane16_swap_b32_e32 v123, v125
	global_store_dwordx4 v[80:81], v[122:125], off offset:384
	v_mul_f32_e32 v52, v52, v66
	v_mul_f32_e32 v53, v53, v66
	v_cvt_pk_bf16_f32 v126, v52, v53
	v_mul_f32_e32 v54, v54, v66
	v_mul_f32_e32 v55, v55, v66
	v_cvt_pk_bf16_f32 v127, v54, v55
	v_mul_f32_e32 v48, v48, v66
	v_mul_f32_e32 v49, v49, v66
	v_cvt_pk_bf16_f32 v128, v48, v49
	v_mul_f32_e32 v50, v50, v66
	v_mul_f32_e32 v51, v51, v66
	v_cvt_pk_bf16_f32 v129, v50, v51
	s_nop 1
	v_permlane16_swap_b32_e32 v126, v128
	v_permlane16_swap_b32_e32 v127, v129
	global_store_dwordx4 v[80:81], v[126:129], off offset:448
	s_waitcnt lgkmcnt(0)
	s_cbranch_scc1 .LBB0_235
	v_readlane_b32 s16, v253, 49
	s_mov_b64 s[36:37], 0xc000800

.LBB0_359:
	s_andn2_b64 vcc, exec, s[22:23]
	s_cbranch_vccnz .LBB0_414
	v_mov_b32_e32 v0, v242
	s_load_dword s9, s[54:55], 0x0
	s_mov_b32 s3, s76
	v_readfirstlane_b32 s0, v0
	s_waitcnt lgkmcnt(0)
	s_ashr_i32 s11, s0, 6
	s_lshl_b32 s0, s3, 3
	s_add_i32 s0, s0, s11
	s_cmpk_gt_i32 s0, 0xfff
	s_cbranch_scc1 .LBB0_363
	s_lshl_b32 s2, s9, 3
	s_lshl_b32 s17, s56, 19
	s_add_u32 s18, s84, s17
	v_bfe_u32 v3, v0, 4, 2
	v_and_b32_e32 v158, 15, v0
	s_addc_u32 s19, s85, 0
	v_lshlrev_b32_e32 v208, 4, v3
	v_lshl_add_u64 v[0:1], s[18:19], 0, v[208:209]
	v_lshlrev_b32_e32 v208, 7, v158
	v_lshl_add_u64 v[0:1], v[0:1], 0, v[208:209]
	s_mov_b64 s[18:19], 0x128000
	v_lshl_add_u64 v[80:81], v[0:1], 0, s[18:19]
	s_mov_b64 s[18:19], 0x129000
	v_lshl_add_u64 v[82:83], v[0:1], 0, s[18:19]
	s_mov_b64 s[18:19], 0x129800
	v_lshl_add_u64 v[84:85], v[0:1], 0, s[18:19]
	s_mov_b64 s[18:19], 0x129040
	v_lshl_add_u64 v[104:105], v[0:1], 0, s[18:19]
	s_mov_b64 s[18:19], 0x129840
	v_lshl_add_u64 v[106:107], v[0:1], 0, s[18:19]
	s_mov_b64 s[18:19], 0x12a000
	v_lshl_add_u64 v[108:109], v[0:1], 0, s[18:19]
	s_mov_b64 s[18:19], 0x12a800
	v_lshl_add_u64 v[110:111], v[0:1], 0, s[18:19]
	s_mov_b64 s[18:19], 0x12b000
	v_lshl_add_u64 v[112:113], v[0:1], 0, s[18:19]
	s_mov_b64 s[18:19], 0x12b800
	v_lshl_add_u64 v[114:115], v[0:1], 0, s[18:19]
	s_mov_b64 s[18:19], 0x12a040
	v_lshl_add_u64 v[116:117], v[0:1], 0, s[18:19]
	s_mov_b64 s[18:19], 0x12a840
	v_lshl_add_u64 v[118:119], v[0:1], 0, s[18:19]
	s_mov_b64 s[18:19], 0x12b040
	v_lshl_add_u64 v[120:121], v[0:1], 0, s[18:19]
	s_mov_b64 s[18:19], 0x12b840
	v_lshl_add_u64 v[122:123], v[0:1], 0, s[18:19]
	s_mov_b64 s[18:19], 0x12c000
	v_lshl_add_u64 v[124:125], v[0:1], 0, s[18:19]
	s_mov_b64 s[18:19], 0x12c800
	v_lshl_add_u64 v[126:127], v[0:1], 0, s[18:19]
	s_mov_b64 s[18:19], 0x12d000
	v_lshl_add_u64 v[128:129], v[0:1], 0, s[18:19]
	s_mov_b64 s[18:19], 0x12d800
	v_lshl_add_u64 v[130:131], v[0:1], 0, s[18:19]
	s_mov_b64 s[18:19], 0x12c040
	v_lshl_add_u64 v[132:133], v[0:1], 0, s[18:19]
	s_mov_b64 s[18:19], 0x12c840
	v_lshl_add_u64 v[134:135], v[0:1], 0, s[18:19]
	s_mov_b64 s[18:19], 0x12d040
	v_lshl_add_u64 v[136:137], v[0:1], 0, s[18:19]
	s_mov_b64 s[18:19], 0x12d840
	v_lshl_add_u64 v[138:139], v[0:1], 0, s[18:19]
	s_mov_b64 s[18:19], 0x12e000
	v_lshl_add_u64 v[140:141], v[0:1], 0, s[18:19]
	s_mov_b64 s[18:19], 0x12e800
	v_lshl_add_u64 v[142:143], v[0:1], 0, s[18:19]
	s_mov_b64 s[18:19], 0x12f000
	v_lshl_add_u64 v[144:145], v[0:1], 0, s[18:19]
	s_mov_b64 s[18:19], 0x12f800
	v_lshl_add_u64 v[146:147], v[0:1], 0, s[18:19]
	s_mov_b64 s[18:19], 0x12e040
	v_lshl_add_u64 v[148:149], v[0:1], 0, s[18:19]
	s_mov_b64 s[18:19], 0x12e840
	v_lshl_add_u64 v[150:151], v[0:1], 0, s[18:19]
	s_mov_b64 s[18:19], 0x12f040
	v_lshlrev_b32_e32 v2, 2, v3
	v_lshlrev_b32_e32 v64, 18, v3
	v_lshl_add_u64 v[152:153], v[0:1], 0, s[18:19]
	s_mov_b64 s[18:19], 0x12f840
	s_lshl_b32 s3, s3, 7
	s_lshl_b32 s11, s11, 4
	v_mov_b32_e32 v65, v209
	v_or_b32_e32 v66, 0x8000, v64
	v_mov_b32_e32 v67, v209
	v_or_b32_e32 v68, 0x10000, v64
	v_mov_b32_e32 v69, v209
	v_or_b32_e32 v70, 0x18000, v64
	v_mov_b32_e32 v71, v209
	v_or_b32_e32 v72, 0x20000, v64
	v_mov_b32_e32 v73, v209
	v_or_b32_e32 v74, 0x28000, v64
	v_mov_b32_e32 v75, v209
	v_or_b32_e32 v76, 0x30000, v64
	v_mov_b32_e32 v77, v209
	v_or_b32_e32 v78, 0x38000, v64
	v_mov_b32_e32 v79, v209
	v_cmp_eq_u32_e32 vcc, 0, v3
	v_sub_u32_e32 v86, 0x100000, v64
	v_mov_b32_e32 v87, v209
	v_or_b32_e32 v88, 0x100000, v64
	v_mov_b32_e32 v89, v209
	v_xor_b32_e32 v90, 0xf8000, v64
	v_mov_b32_e32 v91, v209
	v_xor_b32_e32 v92, 0xf0000, v64
	v_mov_b32_e32 v93, v209
	v_xor_b32_e32 v94, 0xe8000, v64
	v_mov_b32_e32 v95, v209
	v_xor_b32_e32 v96, 0xe0000, v64
	v_mov_b32_e32 v97, v209
	v_xor_b32_e32 v98, 0xd8000, v64
	v_mov_b32_e32 v99, v209
	v_xor_b32_e32 v100, 0xd0000, v64
	v_mov_b32_e32 v101, v209
	v_xor_b32_e32 v102, 0xc8000, v64
	v_mov_b32_e32 v103, v209
	v_lshl_add_u64 v[154:155], v[0:1], 0, s[18:19]
	s_add_i32 s3, s3, s11
	s_lshl_b32 s9, s9, 7
	v_lshlrev_b32_e32 v156, 1, v2
	global_load_dwordx4 v[176:179], v[80:81], off offset:64
	global_load_dwordx4 v[180:183], v[80:81], off offset:2112
	global_load_dwordx4 v[184:187], v[104:105], off
	global_load_dwordx4 v[188:191], v[106:107], off
	global_load_dwordx4 v[192:195], v[116:117], off
	global_load_dwordx4 v[196:199], v[118:119], off
	global_load_dwordx4 v[200:203], v[120:121], off
	global_load_dwordx4 v[204:207], v[122:123], off
	global_load_dwordx4 v[214:217], v[132:133], off
	global_load_dwordx4 v[218:221], v[134:135], off
	global_load_dwordx4 v[222:225], v[136:137], off
	global_load_dwordx4 v[226:229], v[138:139], off
	global_load_dwordx4 v[230:233], v[148:149], off
	global_load_dwordx4 v[234:237], v[150:151], off
	global_load_dwordx4 v[238:241], v[152:153], off
	global_load_dwordx4 v[246:249], v[154:155], off
.LBB0_362:
	global_load_dwordx4 v[104:107], v[80:81], off
	global_load_dwordx4 v[116:119], v[80:81], off offset:2048
	global_load_dwordx4 v[120:123], v[82:83], off
	global_load_dwordx4 v[132:135], v[84:85], off
	s_ashr_i32 s11, s3, 31
	s_lshr_b32 s11, s11, 19
	s_add_i32 s11, s3, s11
	s_and_b32 s11, s11, 0xffffe000
	s_sub_i32 s11, s3, s11
	v_or_b32_e32 v0, s11, v158
	s_ashr_i32 s11, s0, 31
	s_lshr_b32 s11, s11, 23
	s_add_i32 s11, s0, s11
	s_ashr_i32 s11, s11, 9
	s_mul_i32 s18, s11, 0x84
	s_ashr_i32 s19, s18, 31
	v_sub_u32_e32 v1, 0, v0
	s_lshl_b64 s[18:19], s[18:19], 15
	v_and_b32_e32 v2, 0x1fff, v1
	v_ashrrev_i32_e32 v1, 31, v0
	s_add_u32 s22, s16, s18
	s_addc_u32 s23, s33, s19
	v_lshlrev_b64 v[56:57], 2, v[0:1]
	v_lshlrev_b32_e32 v208, 2, v2
	s_mov_b32 s100, 0x0
	v_add3_u32 v252, v56, v64, s100
	global_load_dword v136, v252, s[22:23]
	v_add3_u32 v252, v56, v66, s100
	global_load_dword v137, v252, s[22:23]
	v_add3_u32 v252, v56, v68, s100
	global_load_dword v138, v252, s[22:23]
	v_add3_u32 v252, v56, v70, s100
	global_load_dword v139, v252, s[22:23]
	v_add3_u32 v252, v56, v72, s100
	global_load_dword v148, v252, s[22:23]
	v_add3_u32 v252, v56, v74, s100
	global_load_dword v149, v252, s[22:23]
	v_add3_u32 v252, v56, v76, s100
	global_load_dword v150, v252, s[22:23]
	v_add3_u32 v252, v56, v78, s100
	global_load_dword v151, v252, s[22:23]
	s_mov_b32 s100, 0x0
	v_add3_u32 v252, v56, v88, s100
	v_add3_u32 v169, v208, v86, s100
	v_cndmask_b32_e32 v252, v169, v252, vcc
	global_load_dword v152, v252, s[22:23]
	v_add3_u32 v252, v208, v90, s100
	global_load_dword v153, v252, s[22:23]
	v_add3_u32 v252, v208, v92, s100
	global_load_dword v154, v252, s[22:23]
	v_add3_u32 v252, v208, v94, s100
	global_load_dword v155, v252, s[22:23]
	v_add3_u32 v252, v208, v96, s100
	global_load_dword v250, v252, s[22:23]
	v_add3_u32 v252, v208, v98, s100
	global_load_dword v251, v252, s[22:23]
	v_add3_u32 v252, v208, v100, s100
	global_load_dword v170, v252, s[22:23]
	v_add3_u32 v252, v208, v102, s100
	global_load_dword v171, v252, s[22:23]
	s_mov_b32 s100, 0x108000
	v_add3_u32 v252, v56, v64, s100
	global_load_dword v172, v252, s[22:23]
	v_add3_u32 v252, v56, v66, s100
	global_load_dword v173, v252, s[22:23]
	v_add3_u32 v252, v56, v68, s100
	global_load_dword v174, v252, s[22:23]
	v_add3_u32 v252, v56, v70, s100
	global_load_dword v175, v252, s[22:23]
	v_add3_u32 v252, v56, v72, s100
	global_load_dword v65, v252, s[22:23]
	v_add3_u32 v252, v56, v74, s100
	global_load_dword v67, v252, s[22:23]
	v_add3_u32 v252, v56, v76, s100
	global_load_dword v69, v252, s[22:23]
	v_add3_u32 v252, v56, v78, s100
	global_load_dword v71, v252, s[22:23]
	s_mov_b64 s[18:19], 0x1a000400
	s_add_i32 s0, s0, s2
	s_waitcnt vmcnt(16)
	v_cvt_pk_bf16_f32 v0, v136, v137
	v_cvt_pk_bf16_f32 v1, v138, v139
	v_cvt_pk_bf16_f32 v2, v148, v149
	v_cvt_pk_bf16_f32 v3, v150, v151
	s_mov_b32 s100, 0x108000
	v_add3_u32 v252, v56, v88, s100
	v_add3_u32 v169, v208, v86, s100
	v_cndmask_b32_e32 v252, v169, v252, vcc
	global_load_dword v136, v252, s[22:23]
	v_add3_u32 v252, v208, v90, s100
	global_load_dword v137, v252, s[22:23]
	v_add3_u32 v252, v208, v92, s100
	global_load_dword v138, v252, s[22:23]
	v_add3_u32 v252, v208, v94, s100
	global_load_dword v139, v252, s[22:23]
	v_add3_u32 v252, v208, v96, s100
	global_load_dword v148, v252, s[22:23]
	v_add3_u32 v252, v208, v98, s100
	global_load_dword v149, v252, s[22:23]
	v_add3_u32 v252, v208, v100, s100
	global_load_dword v150, v252, s[22:23]
	v_add3_u32 v252, v208, v102, s100
	global_load_dword v151, v252, s[22:23]
	v_mfma_f32_16x16x32_bf16 v[4:7], v[104:107], v[0:3], 0
	v_mfma_f32_16x16x32_bf16 v[8:11], v[116:119], v[0:3], 0
	v_mfma_f32_16x16x32_bf16 v[12:15], v[120:123], v[0:3], 0
	v_mfma_f32_16x16x32_bf16 v[0:3], v[132:135], v[0:3], 0
	global_load_dwordx4 v[104:107], v[112:113], off
	global_load_dwordx4 v[116:119], v[108:109], off
	global_load_dwordx4 v[120:123], v[110:111], off
	global_load_dwordx4 v[132:135], v[114:115], off
	s_waitcnt vmcnt(20)
	v_cvt_pk_bf16_f32 v16, v152, v153
	v_cvt_pk_bf16_f32 v17, v154, v155
	v_cvt_pk_bf16_f32 v18, v250, v251
	v_cvt_pk_bf16_f32 v19, v170, v171
	s_mov_b32 s100, 0x210000
	v_add3_u32 v252, v56, v64, s100
	global_load_dword v152, v252, s[22:23]
	v_add3_u32 v252, v56, v66, s100
	global_load_dword v153, v252, s[22:23]
	v_add3_u32 v252, v56, v68, s100
	global_load_dword v154, v252, s[22:23]
	v_add3_u32 v252, v56, v70, s100
	global_load_dword v155, v252, s[22:23]
	v_add3_u32 v252, v56, v72, s100
	global_load_dword v250, v252, s[22:23]
	v_add3_u32 v252, v56, v74, s100
	global_load_dword v251, v252, s[22:23]
	v_add3_u32 v252, v56, v76, s100
	global_load_dword v170, v252, s[22:23]
	v_add3_u32 v252, v56, v78, s100
	global_load_dword v171, v252, s[22:23]
	v_mfma_f32_16x16x32_bf16 v[24:27], v[176:179], v[16:19], v[4:7]
	s_nop 2
	v_mfma_f32_16x16x32_bf16 v[8:11], v[180:183], v[16:19], v[8:11]
	v_mfma_f32_16x16x32_bf16 v[4:7], v[184:187], v[16:19], v[12:15]
	s_nop 2
	v_mfma_f32_16x16x32_bf16 v[0:3], v[188:191], v[16:19], v[0:3]
	s_waitcnt vmcnt(8)
	v_cvt_pk_bf16_f32 v12, v172, v173
	v_cvt_pk_bf16_f32 v13, v174, v175
	v_cvt_pk_bf16_f32 v14, v65, v67
	v_cvt_pk_bf16_f32 v15, v69, v71
	s_mov_b32 s100, 0x210000
	v_add3_u32 v252, v56, v88, s100
	v_add3_u32 v169, v208, v86, s100
	v_cndmask_b32_e32 v252, v169, v252, vcc
	global_load_dword v172, v252, s[22:23]
	v_add3_u32 v252, v208, v90, s100
	global_load_dword v173, v252, s[22:23]
	v_add3_u32 v252, v208, v92, s100
	global_load_dword v174, v252, s[22:23]
	v_add3_u32 v252, v208, v94, s100
	global_load_dword v175, v252, s[22:23]
	v_add3_u32 v252, v208, v96, s100
	global_load_dword v65, v252, s[22:23]
	v_add3_u32 v252, v208, v98, s100
	global_load_dword v67, v252, s[22:23]
	v_add3_u32 v252, v208, v100, s100
	global_load_dword v69, v252, s[22:23]
	v_add3_u32 v252, v208, v102, s100
	global_load_dword v71, v252, s[22:23]
	v_mfma_f32_16x16x32_bf16 v[32:35], v[104:107], v[12:15], 0
	v_mfma_f32_16x16x32_bf16 v[16:19], v[116:119], v[12:15], 0
	v_mfma_f32_16x16x32_bf16 v[20:23], v[120:123], v[12:15], 0
	v_mfma_f32_16x16x32_bf16 v[12:15], v[132:135], v[12:15], 0
	global_load_dwordx4 v[104:107], v[128:129], off
	global_load_dwordx4 v[116:119], v[124:125], off
	global_load_dwordx4 v[120:123], v[126:127], off
	global_load_dwordx4 v[132:135], v[130:131], off
	s_waitcnt vmcnt(24)
	v_cvt_pk_bf16_f32 v36, v136, v137
	v_cvt_pk_bf16_f32 v37, v138, v139
	v_cvt_pk_bf16_f32 v38, v148, v149
	v_cvt_pk_bf16_f32 v39, v150, v151
	s_mov_b32 s100, 0x318000
	v_add3_u32 v252, v56, v64, s100
	global_load_dword v136, v252, s[22:23]
	v_add3_u32 v252, v56, v66, s100
	global_load_dword v137, v252, s[22:23]
	v_add3_u32 v252, v56, v68, s100
	global_load_dword v138, v252, s[22:23]
	v_add3_u32 v252, v56, v70, s100
	global_load_dword v139, v252, s[22:23]
	v_add3_u32 v252, v56, v72, s100
	global_load_dword v148, v252, s[22:23]
	v_add3_u32 v252, v56, v74, s100
	global_load_dword v149, v252, s[22:23]
	v_add3_u32 v252, v56, v76, s100
	global_load_dword v150, v252, s[22:23]
	v_add3_u32 v252, v56, v78, s100
	global_load_dword v151, v252, s[22:23]
	v_mfma_f32_16x16x32_bf16 v[28:31], v[192:195], v[36:39], v[16:19]
	s_nop 2
	v_mfma_f32_16x16x32_bf16 v[20:23], v[196:199], v[36:39], v[20:23]
	v_mfma_f32_16x16x32_bf16 v[16:19], v[200:203], v[36:39], v[32:35]
	s_nop 2
	v_mfma_f32_16x16x32_bf16 v[12:15], v[204:207], v[36:39], v[12:15]
	s_waitcnt vmcnt(8)
	v_cvt_pk_bf16_f32 v32, v152, v153
	v_cvt_pk_bf16_f32 v33, v154, v155
	v_cvt_pk_bf16_f32 v34, v250, v251
	v_cvt_pk_bf16_f32 v35, v170, v171
	s_mov_b32 s100, 0x318000
	v_add3_u32 v252, v56, v88, s100
	v_add3_u32 v169, v208, v86, s100
	v_cndmask_b32_e32 v252, v169, v252, vcc
	global_load_dword v152, v252, s[22:23]
	v_add3_u32 v252, v208, v90, s100
	global_load_dword v153, v252, s[22:23]
	v_add3_u32 v252, v208, v92, s100
	global_load_dword v154, v252, s[22:23]
	v_add3_u32 v252, v208, v94, s100
	global_load_dword v155, v252, s[22:23]
	v_add3_u32 v252, v208, v96, s100
	global_load_dword v250, v252, s[22:23]
	v_add3_u32 v252, v208, v98, s100
	global_load_dword v251, v252, s[22:23]
	v_add3_u32 v252, v208, v100, s100
	global_load_dword v170, v252, s[22:23]
	v_add3_u32 v252, v208, v102, s100
	global_load_dword v171, v252, s[22:23]
	v_mfma_f32_16x16x32_bf16 v[48:51], v[104:107], v[32:35], 0
	v_mfma_f32_16x16x32_bf16 v[36:39], v[116:119], v[32:35], 0
	v_mfma_f32_16x16x32_bf16 v[40:43], v[120:123], v[32:35], 0
	v_mfma_f32_16x16x32_bf16 v[32:35], v[132:135], v[32:35], 0
	global_load_dwordx4 v[104:107], v[144:145], off
	global_load_dwordx4 v[116:119], v[140:141], off
	global_load_dwordx4 v[120:123], v[142:143], off
	global_load_dwordx4 v[132:135], v[146:147], off
	s_waitcnt vmcnt(24)
	v_cvt_pk_bf16_f32 v52, v172, v173
	v_cvt_pk_bf16_f32 v53, v174, v175
	v_cvt_pk_bf16_f32 v54, v65, v67
	v_cvt_pk_bf16_f32 v55, v69, v71
	s_nop 1
	v_mfma_f32_16x16x32_bf16 v[44:47], v[214:217], v[52:55], v[36:39]
	s_nop 2
	v_mfma_f32_16x16x32_bf16 v[40:43], v[218:221], v[52:55], v[40:43]
	v_mfma_f32_16x16x32_bf16 v[36:39], v[222:225], v[52:55], v[48:51]
	s_nop 2
	v_mfma_f32_16x16x32_bf16 v[32:35], v[226:229], v[52:55], v[32:35]
	s_waitcnt vmcnt(0)
	v_cvt_pk_bf16_f32 v48, v136, v137
	v_cvt_pk_bf16_f32 v49, v138, v139
	v_cvt_pk_bf16_f32 v50, v148, v149
	v_cvt_pk_bf16_f32 v51, v150, v151
	s_nop 1
	v_mfma_f32_16x16x32_bf16 v[160:163], v[104:107], v[48:51], 0
	v_mfma_f32_16x16x32_bf16 v[52:55], v[116:119], v[48:51], 0
	v_mfma_f32_16x16x32_bf16 v[56:59], v[120:123], v[48:51], 0
	v_mfma_f32_16x16x32_bf16 v[48:51], v[132:135], v[48:51], 0
	s_waitcnt vmcnt(4)
	v_cvt_pk_bf16_f32 v164, v152, v153
	v_cvt_pk_bf16_f32 v165, v154, v155
	v_cvt_pk_bf16_f32 v166, v250, v251
	v_cvt_pk_bf16_f32 v167, v170, v171
	s_nop 1
	v_mul_f32_e32 v157, v0, v0
	v_mul_f32_e32 v159, v1, v1
	v_mfma_f32_16x16x32_bf16 v[60:63], v[230:233], v[164:167], v[52:55]
	s_nop 2
	v_mfma_f32_16x16x32_bf16 v[56:59], v[234:237], v[164:167], v[56:59]
	v_mfma_f32_16x16x32_bf16 v[52:55], v[238:241], v[164:167], v[160:163]
	s_nop 2
	v_mfma_f32_16x16x32_bf16 v[48:51], v[246:249], v[164:167], v[48:51]
	v_mul_f32_e64 v160, v26, v26
	v_mul_f32_e64 v161, v27, v27
	v_pk_mul_f32 v[162:163], v[24:25], v[24:25]
	s_nop 0
	v_pk_mov_b32 v[164:165], v[162:163], v[160:161] op_sel:[1,0]
	v_mov_b32_e32 v163, v161
	v_pk_add_f32 v[160:161], v[164:165], v[162:163]
	v_pk_mul_f32 v[162:163], v[10:11], v[10:11]
	v_pk_mul_f32 v[164:165], v[8:9], v[8:9]
	v_pk_add_f32 v[160:161], v[160:161], v[160:161] op_sel:[0,1] op_sel_hi:[1,0]
	v_pk_mov_b32 v[166:167], v[164:165], v[162:163] op_sel:[1,0]
	v_mov_b32_e32 v165, v163
	v_pk_add_f32 v[162:163], v[166:167], v[164:165]
	v_mov_b32_e32 v161, v157
	v_pk_add_f32 v[162:163], v[162:163], v[162:163] op_sel:[0,1] op_sel_hi:[1,0]
	v_mul_f32_e32 v164, v2, v2
	v_mov_b32_e32 v163, v159
	v_pk_add_f32 v[160:161], v[160:161], v[162:163]
	v_mul_f32_e32 v162, v5, v5
	v_pk_fma_f32 v[162:163], v[4:5], v[4:5], v[162:163] op_sel_hi:[1,1,0]
	v_mul_f32_e32 v166, v3, v3
	v_mov_b32_e32 v163, v164
	v_mul_f32_e32 v164, v7, v7
	v_pk_fma_f32 v[164:165], v[6:7], v[6:7], v[164:165] op_sel_hi:[1,1,0]
	v_mul_f32_e32 v157, v16, v16
	v_mov_b32_e32 v165, v166
	v_pk_add_f32 v[162:163], v[162:163], v[164:165]
	v_pk_mul_f32 v[164:165], v[28:29], v[28:29]
	v_pk_add_f32 v[160:161], v[160:161], v[162:163]
	v_pk_mul_f32 v[162:163], v[30:31], v[30:31]
	v_mul_f32_e32 v159, v17, v17
	v_pk_mov_b32 v[166:167], v[164:165], v[162:163] op_sel:[1,0]
	v_mov_b32_e32 v165, v163
	v_pk_add_f32 v[162:163], v[166:167], v[164:165]
	v_pk_add_f32 v[160:161], v[160:161], v[160:161] op_sel:[0,1] op_sel_hi:[1,0]
	v_pk_add_f32 v[162:163], v[162:163], v[162:163] op_sel:[0,1] op_sel_hi:[1,0]
	v_mov_b32_e32 v161, v157
	v_mov_b32_e32 v163, v159
	v_pk_add_f32 v[160:161], v[160:161], v[162:163]
	v_mul_f32_e32 v162, v21, v21
	v_mul_f32_e32 v164, v18, v18
	v_pk_fma_f32 v[162:163], v[20:21], v[20:21], v[162:163] op_sel_hi:[1,1,0]
	v_mul_f32_e32 v166, v19, v19
	v_mov_b32_e32 v163, v164
	v_mul_f32_e32 v164, v23, v23
	v_pk_fma_f32 v[164:165], v[22:23], v[22:23], v[164:165] op_sel_hi:[1,1,0]
	v_mul_f32_e32 v157, v40, v40
	v_mov_b32_e32 v165, v166
	v_pk_add_f32 v[162:163], v[162:163], v[164:165]
	v_pk_mul_f32 v[164:165], v[12:13], v[12:13]
	v_pk_add_f32 v[160:161], v[160:161], v[162:163]
	v_pk_mul_f32 v[162:163], v[14:15], v[14:15]
	v_mul_f32_e32 v159, v41, v41
	v_pk_mov_b32 v[166:167], v[164:165], v[162:163] op_sel:[1,0]
	v_mov_b32_e32 v165, v163
	v_pk_add_f32 v[162:163], v[166:167], v[164:165]
	v_pk_add_f32 v[160:161], v[160:161], v[160:161] op_sel:[0,1] op_sel_hi:[1,0]
	v_pk_add_f32 v[162:163], v[162:163], v[162:163] op_sel:[0,1] op_sel_hi:[1,0]
	v_mov_b32_e32 v161, v157
	v_mov_b32_e32 v163, v159
	v_pk_add_f32 v[160:161], v[160:161], v[162:163]
	v_mul_f32_e32 v162, v45, v45
	v_mul_f32_e32 v164, v42, v42
	v_pk_fma_f32 v[162:163], v[44:45], v[44:45], v[162:163] op_sel_hi:[1,1,0]
	v_mul_f32_e32 v166, v43, v43
	v_mov_b32_e32 v163, v164
	v_mul_f32_e32 v164, v47, v47
	v_pk_fma_f32 v[164:165], v[46:47], v[46:47], v[164:165] op_sel_hi:[1,1,0]
	v_mul_f32_e32 v157, v60, v60
	v_mov_b32_e32 v165, v166
	v_pk_add_f32 v[162:163], v[162:163], v[164:165]
	v_pk_mul_f32 v[164:165], v[36:37], v[36:37]
	v_pk_add_f32 v[160:161], v[160:161], v[162:163]
	v_pk_mul_f32 v[162:163], v[38:39], v[38:39]
	v_mul_f32_e32 v159, v61, v61
	v_pk_mov_b32 v[166:167], v[164:165], v[162:163] op_sel:[1,0]
	v_mov_b32_e32 v165, v163
	v_pk_add_f32 v[162:163], v[166:167], v[164:165]
	v_pk_add_f32 v[160:161], v[160:161], v[160:161] op_sel:[0,1] op_sel_hi:[1,0]
	v_pk_add_f32 v[162:163], v[162:163], v[162:163] op_sel:[0,1] op_sel_hi:[1,0]
	v_mov_b32_e32 v161, v157
	v_mov_b32_e32 v163, v159
	v_pk_add_f32 v[160:161], v[160:161], v[162:163]
	v_mul_f32_e32 v162, v33, v33
	v_mul_f32_e32 v164, v62, v62
	v_pk_fma_f32 v[162:163], v[32:33], v[32:33], v[162:163] op_sel_hi:[1,1,0]
	v_mul_f32_e32 v166, v63, v63
	v_mov_b32_e32 v163, v164
	v_mul_f32_e32 v164, v35, v35
	v_pk_fma_f32 v[164:165], v[34:35], v[34:35], v[164:165] op_sel_hi:[1,1,0]
	v_mul_f32_e32 v157, v48, v48
	v_mov_b32_e32 v165, v166
	v_pk_add_f32 v[162:163], v[162:163], v[164:165]
	v_pk_mul_f32 v[164:165], v[56:57], v[56:57]
	v_pk_add_f32 v[160:161], v[160:161], v[162:163]
	v_pk_mul_f32 v[162:163], v[58:59], v[58:59]
	v_mul_f32_e32 v159, v49, v49
	v_pk_mov_b32 v[166:167], v[164:165], v[162:163] op_sel:[1,0]
	v_mov_b32_e32 v165, v163
	v_pk_add_f32 v[162:163], v[166:167], v[164:165]
	v_pk_add_f32 v[160:161], v[160:161], v[160:161] op_sel:[0,1] op_sel_hi:[1,0]
	v_pk_add_f32 v[162:163], v[162:163], v[162:163] op_sel:[0,1] op_sel_hi:[1,0]
	v_mov_b32_e32 v161, v157
	v_mov_b32_e32 v163, v159
	v_pk_add_f32 v[160:161], v[160:161], v[162:163]
	v_mul_f32_e32 v162, v53, v53
	v_mul_f32_e32 v164, v50, v50
	v_pk_fma_f32 v[162:163], v[52:53], v[52:53], v[162:163] op_sel_hi:[1,1,0]
	v_mul_f32_e32 v166, v51, v51
	v_mov_b32_e32 v163, v164
	v_mul_f32_e32 v164, v55, v55
	v_pk_fma_f32 v[164:165], v[54:55], v[54:55], v[164:165] op_sel_hi:[1,1,0]
	v_xor_b32_e32 v159, 16, v245
	v_mov_b32_e32 v165, v166
	v_pk_add_f32 v[162:163], v[162:163], v[164:165]
	s_nop 0
	v_pk_add_f32 v[160:161], v[160:161], v[162:163]
	s_nop 0
	v_add_f32_e32 v157, v160, v161
	v_and_b32_e32 v160, 64, v245
	v_add_u32_e32 v160, 64, v160
	v_cmp_lt_i32_e64 s[36:37], v159, v160
	s_nop 1
	v_cndmask_b32_e64 v159, v245, v159, s[36:37]
	v_lshlrev_b32_e32 v159, 2, v159
	ds_bpermute_b32 v159, v159, v157
	s_waitcnt lgkmcnt(0)
	v_add_f32_e32 v157, v157, v159
	v_xor_b32_e32 v159, 32, v245
	v_cmp_lt_i32_e64 s[36:37], v159, v160
	v_add_u32_e32 v160, s3, v158
	v_ashrrev_i32_e32 v161, 31, v160
	v_cndmask_b32_e64 v159, v245, v159, s[36:37]
	v_lshlrev_b32_e32 v159, 2, v159
	ds_bpermute_b32 v159, v159, v157
	v_lshlrev_b64 v[160:161], 11, v[160:161]
	v_lshl_add_u64 v[160:161], s[84:85], 0, v[160:161]
	s_add_i32 s3, s3, s9
	s_cmpk_lt_i32 s0, 0x1000
	s_waitcnt lgkmcnt(0)
	v_add_f32_e32 v157, v157, v159
	v_fmamk_f32 v157, v157, 0x3b800000, v244
	v_cmp_gt_f32_e64 s[36:37], s7, v157
	v_mul_f32_e32 v159, 0x4b800000, v157
	s_nop 0
	v_cndmask_b32_e64 v157, v157, v159, s[36:37]
	v_rsq_f32_e32 v157, v157
	s_nop 0
	v_mul_f32_e32 v159, 0x45800000, v157
	v_cndmask_b32_e64 v159, v157, v159, s[36:37]
	v_mov_b32_e32 v157, v209
	v_lshl_add_u64 v[160:161], v[160:161], 0, v[156:157]
	v_lshl_add_u64 v[162:163], v[160:161], 0, s[18:19]
	v_mbcnt_lo_u32_b32 v154, -1, 0
	v_mbcnt_hi_u32_b32 v154, -1, v154
	v_lshrrev_b32_e32 v154, 4, v154
	v_and_b32_e32 v154, 1, v154
	v_mul_u32_u24_e32 v154, 24, v154
	v_mov_b32_e32 v155, v209
	v_lshl_add_u64 v[152:153], v[162:163], 0, v[154:155]
	v_mul_f32_e32 v24, v24, v159
	v_mul_f32_e32 v25, v25, v159
	v_cvt_pk_bf16_f32 v136, v24, v25
	v_mul_f32_e32 v26, v26, v159
	v_mul_f32_e32 v27, v27, v159
	v_cvt_pk_bf16_f32 v137, v26, v27
	v_mul_f32_e32 v8, v8, v159
	v_mul_f32_e32 v9, v9, v159
	v_cvt_pk_bf16_f32 v138, v8, v9
	v_mul_f32_e32 v10, v10, v159
	v_mul_f32_e32 v11, v11, v159
	v_cvt_pk_bf16_f32 v139, v10, v11
	s_nop 1
	v_permlane16_swap_b32_e32 v136, v138
	v_permlane16_swap_b32_e32 v137, v139
	global_store_dwordx4 v[152:153], v[136:139], off
	v_mul_f32_e32 v4, v4, v159
	v_mul_f32_e32 v5, v5, v159
	v_cvt_pk_bf16_f32 v148, v4, v5
	v_mul_f32_e32 v6, v6, v159
	v_mul_f32_e32 v7, v7, v159
	v_cvt_pk_bf16_f32 v149, v6, v7
	v_mul_f32_e32 v0, v0, v159
	v_mul_f32_e32 v1, v1, v159
	v_cvt_pk_bf16_f32 v150, v0, v1
	v_mul_f32_e32 v2, v2, v159
	v_mul_f32_e32 v3, v3, v159
	v_cvt_pk_bf16_f32 v151, v2, v3
	s_nop 1
	v_permlane16_swap_b32_e32 v148, v150
	v_permlane16_swap_b32_e32 v149, v151
	global_store_dwordx4 v[152:153], v[148:151], off offset:64
	v_mul_f32_e32 v28, v28, v159
	v_mul_f32_e32 v29, v29, v159
	v_cvt_pk_bf16_f32 v136, v28, v29
	v_mul_f32_e32 v30, v30, v159
	v_mul_f32_e32 v31, v31, v159
	v_cvt_pk_bf16_f32 v137, v30, v31
	v_mul_f32_e32 v20, v20, v159
	v_mul_f32_e32 v21, v21, v159
	v_cvt_pk_bf16_f32 v138, v20, v21
	v_mul_f32_e32 v22, v22, v159
	v_mul_f32_e32 v23, v23, v159
	v_cvt_pk_bf16_f32 v139, v22, v23
	s_nop 1
	v_permlane16_swap_b32_e32 v136, v138
	v_permlane16_swap_b32_e32 v137, v139
	global_store_dwordx4 v[152:153], v[136:139], off offset:128
	v_mul_f32_e32 v16, v16, v159
	v_mul_f32_e32 v17, v17, v159
	v_cvt_pk_bf16_f32 v148, v16, v17
	v_mul_f32_e32 v18, v18, v159
	v_mul_f32_e32 v19, v19, v159
	v_cvt_pk_bf16_f32 v149, v18, v19
	v_mul_f32_e32 v12, v12, v159
	v_mul_f32_e32 v13, v13, v159
	v_cvt_pk_bf16_f32 v150, v12, v13
	v_mul_f32_e32 v14, v14, v159
	v_mul_f32_e32 v15, v15, v159
	v_cvt_pk_bf16_f32 v151, v14, v15
	s_nop 1
	v_permlane16_swap_b32_e32 v148, v150
	v_permlane16_swap_b32_e32 v149, v151
	global_store_dwordx4 v[152:153], v[148:151], off offset:192
	v_mul_f32_e32 v44, v44, v159
	v_mul_f32_e32 v45, v45, v159
	v_cvt_pk_bf16_f32 v136, v44, v45
	v_mul_f32_e32 v46, v46, v159
	v_mul_f32_e32 v47, v47, v159
	v_cvt_pk_bf16_f32 v137, v46, v47
	v_mul_f32_e32 v40, v40, v159
	v_mul_f32_e32 v41, v41, v159
	v_cvt_pk_bf16_f32 v138, v40, v41
	v_mul_f32_e32 v42, v42, v159
	v_mul_f32_e32 v43, v43, v159
	v_cvt_pk_bf16_f32 v139, v42, v43
	s_nop 1
	v_permlane16_swap_b32_e32 v136, v138
	v_permlane16_swap_b32_e32 v137, v139
	global_store_dwordx4 v[152:153], v[136:139], off offset:256
	v_mul_f32_e32 v36, v36, v159
	v_mul_f32_e32 v37, v37, v159
	v_cvt_pk_bf16_f32 v148, v36, v37
	v_mul_f32_e32 v38, v38, v159
	v_mul_f32_e32 v39, v39, v159
	v_cvt_pk_bf16_f32 v149, v38, v39
	v_mul_f32_e32 v32, v32, v159
	v_mul_f32_e32 v33, v33, v159
	v_cvt_pk_bf16_f32 v150, v32, v33
	v_mul_f32_e32 v34, v34, v159
	v_mul_f32_e32 v35, v35, v159
	v_cvt_pk_bf16_f32 v151, v34, v35
	s_nop 1
	v_permlane16_swap_b32_e32 v148, v150
	v_permlane16_swap_b32_e32 v149, v151
	global_store_dwordx4 v[152:153], v[148:151], off offset:320
	v_mul_f32_e32 v60, v60, v159
	v_mul_f32_e32 v61, v61, v159
	v_cvt_pk_bf16_f32 v136, v60, v61
	v_mul_f32_e32 v62, v62, v159
	v_mul_f32_e32 v63, v63, v159
	v_cvt_pk_bf16_f32 v137, v62, v63
	v_mul_f32_e32 v56, v56, v159
	v_mul_f32_e32 v57, v57, v159
	v_cvt_pk_bf16_f32 v138, v56, v57
	v_mul_f32_e32 v58, v58, v159
	v_mul_f32_e32 v59, v59, v159
	v_cvt_pk_bf16_f32 v139, v58, v59
	s_nop 1
	v_permlane16_swap_b32_e32 v136, v138
	v_permlane16_swap_b32_e32 v137, v139
	global_store_dwordx4 v[152:153], v[136:139], off offset:384
	v_mul_f32_e32 v52, v52, v159
	v_mul_f32_e32 v53, v53, v159
	v_cvt_pk_bf16_f32 v148, v52, v53
	v_mul_f32_e32 v54, v54, v159
	v_mul_f32_e32 v55, v55, v159
	v_cvt_pk_bf16_f32 v149, v54, v55
	v_mul_f32_e32 v48, v48, v159
	v_mul_f32_e32 v49, v49, v159
	v_cvt_pk_bf16_f32 v150, v48, v49
	v_mul_f32_e32 v50, v50, v159
	v_mul_f32_e32 v51, v51, v159
	v_cvt_pk_bf16_f32 v151, v50, v51
	s_nop 1
	v_permlane16_swap_b32_e32 v148, v150
	v_permlane16_swap_b32_e32 v149, v151
	global_store_dwordx4 v[152:153], v[148:151], off offset:448
	s_cbranch_scc1 .LBB0_362
